# scan chunk loop unrolled x4 with u-row prefetch distance 4 chunks (register ring, no copies)
# speedup vs baseline: 1.0031x; 1.0031x over previous
.LBB0_615:
	s_waitcnt vmcnt(0)
	v_cvt_pk_bf16_f32 v87, v87, v92
	v_cvt_pk_bf16_f32 v92, v89, v90
	v_cvt_pk_bf16_f32 v89, v131, v150
	v_mul_f32_e32 v131, v100, v100
	v_cvt_pk_bf16_f32 v88, v88, v149
	v_fmamk_f32 v149, v131, 0xb94c1982, v180
	v_fmaak_f32 v149, v131, v149, 0xbe2aaa9d
	v_mul_f32_e32 v149, v131, v149
	v_fmac_f32_e32 v100, v100, v149
	v_fmamk_f32 v149, v131, 0x37d75334, v181
	v_fmaak_f32 v149, v131, v149, 0x3d2aabf7
	v_fmaak_f32 v149, v131, v149, 0xbf000004
	v_lshlrev_b32_e32 v150, 30, v115
	v_and_b32_e32 v115, 1, v115
	v_fma_f32 v149, v131, v149, 1.0
	v_cmp_eq_u32_e64 s[46:47], 0, v115
	v_mul_f32_e32 v65, v65, v110
	v_xor_b32_e32 v107, v107, v106
	v_cndmask_b32_e64 v115, v149, v100, s[46:47]
	v_mul_f32_e32 v65, 0x3fb8aa3b, v65
	v_xor_b32_e32 v107, v107, v115
	v_exp_f32_e32 v115, v65
	v_and_b32_e32 v131, 0x80000000, v150
	v_xor_b32_e32 v107, v107, v131
	v_cmp_class_f32_e64 s[48:49], v106, s10
	v_cvt_pk_bf16_f32 v82, v82, v151
	v_xor_b32_e32 v147, v147, v146
	v_cndmask_b32_e64 v106, v191, v107, s[48:49]
	v_mul_f32_e32 v131, v115, v106
	v_mul_f32_e32 v106, v110, v104
	v_mul_f32_e32 v106, 0x3fb8aa3b, v106
	v_exp_f32_e32 v107, v106
	v_mul_f32_e32 v106, v128, v128
	v_fmamk_f32 v151, v106, 0xb94c1982, v180
	v_fmaak_f32 v151, v106, v151, 0xbe2aaa9d
	v_mul_f32_e32 v151, v106, v151
	v_fmac_f32_e32 v128, v128, v151
	v_fmamk_f32 v151, v106, 0x37d75334, v181
	v_fmaak_f32 v151, v106, v151, 0x3d2aabf7
	v_fmaak_f32 v151, v106, v151, 0xbf000004
	v_fma_f32 v106, v106, v151, 1.0
	v_lshlrev_b32_e32 v151, 30, v148
	v_and_b32_e32 v148, 1, v148
	v_cmp_eq_u32_e32 vcc, 0, v148
	v_cvt_pk_bf16_f32 v83, v83, v152
	v_and_b32_e32 v152, 0x80000000, v151
	v_cndmask_b32_e32 v148, v106, v128, vcc
	v_xor_b32_e32 v128, 0x80000000, v128
	v_xor_b32_e32 v147, v147, v148
	v_cndmask_b32_e32 v106, v128, v106, vcc
	v_xor_b32_e32 v147, v147, v152
	v_bitop3_b32 v106, v106, v151, s14 bitop3:0x78
	v_cmp_class_f32_e64 vcc, v146, s10
	v_cvt_pk_bf16_f32 v64, v64, v198
	v_cvt_pk_bf16_f32 v63, v195, v197
	v_cndmask_b32_e32 v106, v191, v106, vcc
	v_cndmask_b32_e32 v128, v191, v147, vcc
	v_pk_mul_f32 v[146:147], v[104:105], v[104:105]
	v_fma_f32 v106, v107, v106, -1.0
	v_mul_f32_e32 v107, v107, v128
	v_add_f32_e32 v128, v146, v147
	v_div_scale_f32 v146, s[96:97], v128, v128, 1.0
	v_rcp_f32_e32 v147, v146
	v_cvt_pk_bf16_f32 v62, v194, v196
	v_cvt_pk_bf16_f32 v68, v68, v175
	v_cvt_pk_bf16_f32 v67, v67, v173
	v_fma_f32 v148, -v146, v147, 1.0
	v_fmac_f32_e32 v147, v148, v147
	v_div_scale_f32 v148, vcc, 1.0, v128, 1.0
	v_mul_f32_e32 v151, v148, v147
	v_fma_f32 v152, -v146, v151, v148
	v_fmac_f32_e32 v151, v152, v147
	v_fma_f32 v146, -v146, v151, v148
	v_div_fmas_f32 v146, v146, v147, v151
	v_div_fixup_f32 v148, v146, v128, 1.0
	v_pk_mul_f32 v[146:147], v[104:105], v[106:107]
	v_cvt_pk_bf16_f32 v66, v66, v171
	v_add_f32_e32 v128, v146, v147
	v_mov_b32_e32 v146, v107
	v_mov_b32_e32 v147, v106
	v_pk_mul_f32 v[104:105], v[104:105], v[146:147]
	v_mul_f32_e32 v128, v148, v128
	v_sub_f32_e32 v104, v104, v105
	v_mul_f32_e32 v104, v148, v104
	v_pk_mul_f32 v[106:107], v[94:95], v[128:129] op_sel_hi:[1,0]
	v_pk_mul_f32 v[94:95], v[94:95], v[104:105] op_sel_hi:[1,0]
	v_pk_fma_f32 v[106:107], v[56:57], v[104:105], v[106:107] op_sel_hi:[1,0,1]
	v_pk_fma_f32 v[56:57], v[56:57], v[128:129], v[94:95] op_sel_hi:[1,0,1] neg_lo:[0,0,1] neg_hi:[0,0,1]
	v_cvt_pk_bf16_f32 v72, v72, v170
	v_mov_b32_e32 v57, v107
	v_mov_b32_e32 v56, v106
	v_cvt_pk_bf16_f32 v94, v56, v57
	v_pk_mul_f32 v[56:57], v[96:97], v[128:129] op_sel_hi:[1,0]
	v_pk_mul_f32 v[96:97], v[96:97], v[104:105] op_sel_hi:[1,0]
	v_pk_fma_f32 v[56:57], v[58:59], v[104:105], v[56:57] op_sel_hi:[1,0,1]
	v_pk_fma_f32 v[58:59], v[58:59], v[128:129], v[96:97] op_sel_hi:[1,0,1] neg_lo:[0,0,1] neg_hi:[0,0,1]
	v_cvt_pk_bf16_f32 v71, v71, v168
	s_nop 0
	s_nop 0
	v_cvt_pk_bf16_f32 v95, v56, v57
	v_pk_mul_f32 v[56:57], v[52:53], v[128:129] op_sel_hi:[1,0]
	v_pk_mul_f32 v[52:53], v[52:53], v[104:105] op_sel_hi:[1,0]
	v_pk_fma_f32 v[56:57], v[48:49], v[104:105], v[56:57] op_sel_hi:[1,0,1]
	v_pk_fma_f32 v[48:49], v[48:49], v[128:129], v[52:53] op_sel_hi:[1,0,1] neg_lo:[0,0,1] neg_hi:[0,0,1]
	v_pk_mul_f32 v[52:53], v[104:105], v[54:55] op_sel_hi:[0,1]
	v_mov_b32_e32 v49, v57
	v_mov_b32_e32 v48, v56
	v_cvt_pk_bf16_f32 v96, v48, v49
	v_pk_mul_f32 v[48:49], v[128:129], v[54:55] op_sel_hi:[0,1]
	v_pk_fma_f32 v[48:49], v[50:51], v[104:105], v[48:49] op_sel_hi:[1,0,1]
	v_pk_fma_f32 v[50:51], v[50:51], v[128:129], v[52:53] op_sel_hi:[1,0,1] neg_lo:[0,0,1] neg_hi:[0,0,1]
	v_and_b32_e32 v52, 1, v145
	s_nop 0
	s_nop 0
	v_cvt_pk_bf16_f32 v97, v48, v49
	v_mul_f32_e32 v48, v110, v102
	v_mul_f32_e32 v48, 0x3fb8aa3b, v48
	v_exp_f32_e32 v49, v48
	v_mul_f32_e32 v48, v144, v144
	v_fmamk_f32 v50, v48, 0xb94c1982, v180
	v_fmaak_f32 v50, v48, v50, 0xbe2aaa9d
	v_mul_f32_e32 v50, v48, v50
	v_fmac_f32_e32 v144, v144, v50
	v_fmamk_f32 v50, v48, 0x37d75334, v181
	v_fmaak_f32 v50, v48, v50, 0x3d2aabf7
	v_fmaak_f32 v50, v48, v50, 0xbf000004
	v_fma_f32 v48, v48, v50, 1.0
	v_cmp_eq_u32_e32 vcc, 0, v52
	v_lshlrev_b32_e32 v50, 30, v145
	v_xor_b32_e32 v53, v143, v142
	v_cndmask_b32_e32 v52, v48, v144, vcc
	v_and_b32_e32 v51, 0x80000000, v50
	v_xor_b32_e32 v52, v53, v52
	v_xor_b32_e32 v51, v52, v51
	v_xor_b32_e32 v52, 0x80000000, v144
	v_cndmask_b32_e32 v48, v52, v48, vcc
	v_bitop3_b32 v48, v48, v50, s14 bitop3:0x78
	v_cmp_class_f32_e64 vcc, v142, s10
	v_cvt_pk_bf16_f32 v70, v70, v166
	v_cvt_pk_bf16_f32 v76, v76, v165
	v_cndmask_b32_e32 v48, v191, v48, vcc
	v_cndmask_b32_e32 v50, v191, v51, vcc
	v_fma_f32 v48, v49, v48, -1.0
	v_mul_f32_e32 v49, v49, v50
	v_pk_mul_f32 v[50:51], v[102:103], v[102:103]
	v_cvt_pk_bf16_f32 v75, v75, v163
	v_add_f32_e32 v50, v50, v51
	v_div_scale_f32 v51, s[96:97], v50, v50, 1.0
	v_rcp_f32_e32 v52, v51
	v_cvt_pk_bf16_f32 v74, v74, v161
	v_cvt_pk_bf16_f32 v80, v80, v159
	v_cvt_pk_bf16_f32 v79, v79, v157
	v_fma_f32 v53, -v51, v52, 1.0
	v_fmac_f32_e32 v52, v53, v52
	v_div_scale_f32 v53, vcc, 1.0, v50, 1.0
	v_mul_f32_e32 v54, v53, v52
	v_fma_f32 v55, -v51, v54, v53
	v_fmac_f32_e32 v54, v55, v52
	v_fma_f32 v51, -v51, v54, v53
	v_div_fmas_f32 v51, v51, v52, v54
	v_mov_b32_e32 v52, v49
	v_mov_b32_e32 v53, v48
	v_div_fixup_f32 v54, v51, v50, 1.0
	v_pk_mul_f32 v[50:51], v[102:103], v[48:49]
	v_pk_mul_f32 v[48:49], v[102:103], v[52:53]
	v_add_f32_e32 v50, v50, v51
	v_sub_f32_e32 v48, v48, v49
	v_mul_f32_e32 v50, v54, v50
	v_mul_f32_e32 v48, v54, v48
	v_pk_mul_f32 v[52:53], v[44:45], v[50:51] op_sel_hi:[1,0]
	v_pk_mul_f32 v[44:45], v[44:45], v[48:49] op_sel_hi:[1,0]
	v_pk_fma_f32 v[52:53], v[40:41], v[48:49], v[52:53] op_sel_hi:[1,0,1]
	v_pk_fma_f32 v[40:41], v[40:41], v[50:51], v[44:45] op_sel_hi:[1,0,1] neg_lo:[0,0,1] neg_hi:[0,0,1]
	v_pk_mul_f32 v[44:45], v[46:47], v[48:49] op_sel_hi:[1,0]
	s_nop 0
	s_nop 0
	v_cvt_pk_bf16_f32 v102, v40, v41
	v_pk_mul_f32 v[40:41], v[46:47], v[50:51] op_sel_hi:[1,0]
	v_cvt_pk_bf16_f32 v78, v78, v156
	v_pk_fma_f32 v[40:41], v[42:43], v[48:49], v[40:41] op_sel_hi:[1,0,1]
	v_pk_fma_f32 v[42:43], v[42:43], v[50:51], v[44:45] op_sel_hi:[1,0,1] neg_lo:[0,0,1] neg_hi:[0,0,1]
	v_cvt_pk_bf16_f32 v84, v84, v154
	v_mov_b32_e32 v41, v43
	v_mov_b32_e32 v40, v42
	v_cvt_pk_bf16_f32 v103, v40, v41
	v_pk_mul_f32 v[40:41], v[36:37], v[50:51] op_sel_hi:[1,0]
	v_pk_mul_f32 v[36:37], v[36:37], v[48:49] op_sel_hi:[1,0]
	v_pk_fma_f32 v[40:41], v[32:33], v[48:49], v[40:41] op_sel_hi:[1,0,1]
	v_pk_fma_f32 v[32:33], v[32:33], v[50:51], v[36:37] op_sel_hi:[1,0,1] neg_lo:[0,0,1] neg_hi:[0,0,1]
	v_pk_mul_f32 v[36:37], v[48:49], v[38:39] op_sel_hi:[0,1]
	s_nop 0
	s_nop 0
	v_cvt_pk_bf16_f32 v104, v32, v33
	v_pk_mul_f32 v[32:33], v[50:51], v[38:39] op_sel_hi:[0,1]
	v_pk_fma_f32 v[32:33], v[34:35], v[48:49], v[32:33] op_sel_hi:[1,0,1]
	v_pk_fma_f32 v[34:35], v[34:35], v[50:51], v[36:37] op_sel_hi:[1,0,1] neg_lo:[0,0,1] neg_hi:[0,0,1]
	v_and_b32_e32 v36, 1, v117
	v_mov_b32_e32 v33, v35
	v_mov_b32_e32 v32, v34
	v_cvt_pk_bf16_f32 v105, v32, v33
	v_mul_f32_e32 v32, v110, v98
	v_mul_f32_e32 v32, 0x3fb8aa3b, v32
	v_exp_f32_e32 v33, v32
	v_mul_f32_e32 v32, v116, v116
	v_fmamk_f32 v34, v32, 0xb94c1982, v180
	v_fmaak_f32 v34, v32, v34, 0xbe2aaa9d
	v_mul_f32_e32 v34, v32, v34
	v_fmac_f32_e32 v116, v116, v34
	v_fmamk_f32 v34, v32, 0x37d75334, v181
	v_fmaak_f32 v34, v32, v34, 0x3d2aabf7
	v_fmaak_f32 v34, v32, v34, 0xbf000004
	v_fma_f32 v32, v32, v34, 1.0
	v_cmp_eq_u32_e32 vcc, 0, v36
	v_lshlrev_b32_e32 v34, 30, v117
	v_xor_b32_e32 v37, v109, v108
	v_cndmask_b32_e32 v36, v32, v116, vcc
	v_and_b32_e32 v35, 0x80000000, v34
	v_xor_b32_e32 v36, v37, v36
	v_xor_b32_e32 v35, v36, v35
	v_xor_b32_e32 v36, 0x80000000, v116
	v_cndmask_b32_e32 v32, v36, v32, vcc
	v_bitop3_b32 v32, v32, v34, s14 bitop3:0x78
	v_cmp_class_f32_e64 vcc, v108, s10
	v_cvt_pk_bf16_f32 v86, v86, v91
	v_cvt_pk_bf16_f32 v91, v69, v81
	v_cndmask_b32_e32 v32, v191, v32, vcc
	v_cndmask_b32_e32 v34, v191, v35, vcc
	v_fma_f32 v32, v33, v32, -1.0
	v_mul_f32_e32 v33, v33, v34
	v_pk_mul_f32 v[34:35], v[98:99], v[98:99]
	v_cvt_pk_bf16_f32 v90, v73, v77
	v_add_f32_e32 v34, v34, v35
	v_div_scale_f32 v35, s[96:97], v34, v34, 1.0
	v_rcp_f32_e32 v36, v35
	v_cvt_pk_bf16_f32 v93, v85, v93
	v_cvt_pk_bf16_f32 v85, v153, v155
	v_cvt_pk_bf16_f32 v81, v158, v160
	v_fma_f32 v37, -v35, v36, 1.0
	v_fmac_f32_e32 v36, v37, v36
	v_div_scale_f32 v37, vcc, 1.0, v34, 1.0
	v_mul_f32_e32 v38, v37, v36
	v_fma_f32 v39, -v35, v38, v37
	v_fmac_f32_e32 v38, v39, v36
	v_fma_f32 v35, -v35, v38, v37
	v_div_fmas_f32 v35, v35, v36, v38
	v_mov_b32_e32 v36, v33
	v_mov_b32_e32 v37, v32
	v_div_fixup_f32 v38, v35, v34, 1.0
	v_pk_mul_f32 v[34:35], v[98:99], v[32:33]
	v_pk_mul_f32 v[32:33], v[98:99], v[36:37]
	v_add_f32_e32 v34, v34, v35
	v_sub_f32_e32 v32, v32, v33
	v_mul_f32_e32 v34, v38, v34
	v_mul_f32_e32 v32, v38, v32
	v_pk_mul_f32 v[36:37], v[28:29], v[34:35] op_sel_hi:[1,0]
	v_pk_mul_f32 v[28:29], v[28:29], v[32:33] op_sel_hi:[1,0]
	v_pk_fma_f32 v[36:37], v[24:25], v[32:33], v[36:37] op_sel_hi:[1,0,1]
	v_pk_fma_f32 v[24:25], v[24:25], v[34:35], v[28:29] op_sel_hi:[1,0,1] neg_lo:[0,0,1] neg_hi:[0,0,1]
	v_pk_mul_f32 v[28:29], v[30:31], v[32:33] op_sel_hi:[1,0]
	v_mov_b32_e32 v25, v37
	v_mov_b32_e32 v24, v36
	v_cvt_pk_bf16_f32 v106, v24, v25
	v_pk_mul_f32 v[24:25], v[30:31], v[34:35] op_sel_hi:[1,0]
	v_cvt_pk_bf16_f32 v77, v162, v164
	v_pk_fma_f32 v[24:25], v[26:27], v[32:33], v[24:25] op_sel_hi:[1,0,1]
	v_pk_fma_f32 v[26:27], v[26:27], v[34:35], v[28:29] op_sel_hi:[1,0,1] neg_lo:[0,0,1] neg_hi:[0,0,1]
	v_cvt_pk_bf16_f32 v73, v167, v169
	s_nop 0
	s_nop 0
	v_cvt_pk_bf16_f32 v107, v24, v25
	v_pk_mul_f32 v[24:25], v[20:21], v[34:35] op_sel_hi:[1,0]
	v_pk_mul_f32 v[20:21], v[20:21], v[32:33] op_sel_hi:[1,0]
	v_pk_fma_f32 v[24:25], v[16:17], v[32:33], v[24:25] op_sel_hi:[1,0,1]
	v_pk_fma_f32 v[16:17], v[16:17], v[34:35], v[20:21] op_sel_hi:[1,0,1] neg_lo:[0,0,1] neg_hi:[0,0,1]
	v_pk_mul_f32 v[20:21], v[32:33], v[22:23] op_sel_hi:[0,1]
	v_mov_b32_e32 v17, v25
	v_mov_b32_e32 v16, v24
	v_cvt_pk_bf16_f32 v108, v16, v17
	v_pk_mul_f32 v[16:17], v[34:35], v[22:23] op_sel_hi:[0,1]
	v_pk_fma_f32 v[16:17], v[18:19], v[32:33], v[16:17] op_sel_hi:[1,0,1]
	v_pk_fma_f32 v[18:19], v[18:19], v[34:35], v[20:21] op_sel_hi:[1,0,1] neg_lo:[0,0,1] neg_hi:[0,0,1]
	v_and_b32_e32 v20, 1, v114
	s_nop 0
	s_nop 0
	v_cvt_pk_bf16_f32 v109, v16, v17
	v_mul_f32_e32 v16, v110, v60
	v_mul_f32_e32 v16, 0x3fb8aa3b, v16
	v_exp_f32_e32 v17, v16
	v_mul_f32_e32 v16, v113, v113
	v_fmamk_f32 v18, v16, 0xb94c1982, v180
	v_fmaak_f32 v18, v16, v18, 0xbe2aaa9d
	v_mul_f32_e32 v18, v16, v18
	v_fmac_f32_e32 v113, v113, v18
	v_fmamk_f32 v18, v16, 0x37d75334, v181
	v_fmaak_f32 v18, v16, v18, 0x3d2aabf7
	v_fmaak_f32 v18, v16, v18, 0xbf000004
	v_fma_f32 v16, v16, v18, 1.0
	v_cmp_eq_u32_e32 vcc, 0, v20
	v_lshlrev_b32_e32 v18, 30, v114
	v_xor_b32_e32 v21, v112, v111
	v_cndmask_b32_e32 v20, v16, v113, vcc
	v_and_b32_e32 v19, 0x80000000, v18
	v_xor_b32_e32 v20, v21, v20
	v_xor_b32_e32 v19, v20, v19
	v_xor_b32_e32 v20, 0x80000000, v113
	v_cndmask_b32_e32 v16, v20, v16, vcc
	v_bitop3_b32 v16, v16, v18, s14 bitop3:0x78
	v_cmp_class_f32_e64 vcc, v111, s10
	v_cvt_pk_bf16_f32 v69, v172, v174
	v_cvt_pk_bf16_f32 v65, v192, v193
	v_cndmask_b32_e32 v16, v191, v16, vcc
	v_cndmask_b32_e32 v18, v191, v19, vcc
	v_fma_f32 v16, v17, v16, -1.0
	v_mul_f32_e32 v17, v17, v18
	v_pk_mul_f32 v[18:19], v[60:61], v[60:61]
	s_nop 0
	v_add_f32_e32 v18, v18, v19
	v_div_scale_f32 v19, s[96:97], v18, v18, 1.0
	v_rcp_f32_e32 v20, v19
	s_nop 0
	v_fma_f32 v21, -v19, v20, 1.0
	v_fmac_f32_e32 v20, v21, v20
	v_div_scale_f32 v21, vcc, 1.0, v18, 1.0
	v_mul_f32_e32 v22, v21, v20
	v_fma_f32 v23, -v19, v22, v21
	v_fmac_f32_e32 v22, v23, v20
	v_fma_f32 v19, -v19, v22, v21
	v_div_fmas_f32 v19, v19, v20, v22
	v_mov_b32_e32 v20, v17
	v_mov_b32_e32 v21, v16
	v_div_fixup_f32 v22, v19, v18, 1.0
	v_pk_mul_f32 v[18:19], v[60:61], v[16:17]
	v_pk_mul_f32 v[16:17], v[60:61], v[20:21]
	v_add_f32_e32 v18, v18, v19
	v_sub_f32_e32 v16, v16, v17
	v_mul_f32_e32 v18, v22, v18
	v_mul_f32_e32 v16, v22, v16
	v_pk_mul_f32 v[20:21], v[12:13], v[18:19] op_sel_hi:[1,0]
	v_pk_mul_f32 v[12:13], v[12:13], v[16:17] op_sel_hi:[1,0]
	v_pk_fma_f32 v[20:21], v[8:9], v[16:17], v[20:21] op_sel_hi:[1,0,1]
	v_pk_fma_f32 v[8:9], v[8:9], v[18:19], v[12:13] op_sel_hi:[1,0,1] neg_lo:[0,0,1] neg_hi:[0,0,1]
	v_pk_mul_f32 v[12:13], v[14:15], v[16:17] op_sel_hi:[1,0]
	s_nop 0
	s_nop 0
	v_cvt_pk_bf16_f32 v110, v8, v9
	v_pk_mul_f32 v[8:9], v[14:15], v[18:19] op_sel_hi:[1,0]
	v_lshlrev_b32_e32 v60, 4, v140
	v_pk_fma_f32 v[8:9], v[10:11], v[16:17], v[8:9] op_sel_hi:[1,0,1]
	v_pk_fma_f32 v[10:11], v[10:11], v[18:19], v[12:13] op_sel_hi:[1,0,1] neg_lo:[0,0,1] neg_hi:[0,0,1]
	v_ashrrev_i32_e32 v61, 31, v60
	v_mov_b32_e32 v9, v11
	v_mov_b32_e32 v8, v10
	v_cvt_pk_bf16_f32 v111, v8, v9
	v_pk_mul_f32 v[8:9], v[4:5], v[18:19] op_sel_hi:[1,0]
	v_pk_mul_f32 v[4:5], v[4:5], v[16:17] op_sel_hi:[1,0]
	v_pk_fma_f32 v[8:9], v[0:1], v[16:17], v[8:9] op_sel_hi:[1,0,1]
	v_pk_fma_f32 v[0:1], v[0:1], v[18:19], v[4:5] op_sel_hi:[1,0,1] neg_lo:[0,0,1] neg_hi:[0,0,1]
	v_pk_mul_f32 v[4:5], v[16:17], v[6:7] op_sel_hi:[0,1]
	s_nop 0
	s_nop 0
	v_cvt_pk_bf16_f32 v112, v0, v1
	v_pk_mul_f32 v[0:1], v[18:19], v[6:7] op_sel_hi:[0,1]
	v_pk_fma_f32 v[0:1], v[2:3], v[16:17], v[0:1] op_sel_hi:[1,0,1]
	v_pk_fma_f32 v[2:3], v[2:3], v[18:19], v[4:5] op_sel_hi:[1,0,1] neg_lo:[0,0,1] neg_hi:[0,0,1]
	s_nop 0
	v_mov_b32_e32 v1, v3
	v_mov_b32_e32 v0, v2
	v_cvt_pk_bf16_f32 v113, v0, v1
	v_xor_b32_e32 v0, 0x80000000, v100
	v_cndmask_b32_e64 v0, v0, v149, s[46:47]
	v_bitop3_b32 v0, v0, v150, s14 bitop3:0x78
	s_lshl_b32 s46, s50, 12
	v_cndmask_b32_e64 v0, v191, v0, s[48:49]
	s_add_i32 s48, s46, 0x2000
	s_lshl_b32 s49, s50, 8
	s_and_b64 s[46:47], s[76:77], exec
	s_cselect_b32 s51, s48, s49
	s_cmp_eq_u32 s38, 0
	s_cselect_b64 s[46:47], -1, 0
	s_and_b64 vcc, s[46:47], exec
	s_mov_b32 s46, 0x27600000
	s_cselect_b32 s46, s46, 0x2c600000
	s_add_u32 s46, s58, s46
	v_mul_f32_e32 v150, v115, v0
	s_addc_u32 s47, s59, 0
	s_mov_b64 s[48:49], -1
	s_cbranch_vccnz .LBB0_622
	v_and_b32_e32 v56, 31, v133
	v_bfe_u32 v57, v133, 5, 1
	v_and_b32_e32 v58, 63, v133
	v_lshl_add_u32 v240, v58, 2, v127
	v_mul_u32_u24_e32 v59, 0x110, v56
	v_lshl_add_u32 v241, v57, 4, v127
	v_add_u32_e32 v241, v241, v59
	s_lshl_b32 s76, s39, 5
	s_add_i32 s76, s76, s51
	s_sub_i32 s76, s76, 32
	v_add_u32_e32 v242, s76, v56
	s_mov_b32 s48, 0xffff0000
	s_mov_b32 s49, -1
	v_mov_b32_e32 v243, 0
	v_lshlrev_b64 v[242:243], 11, v[242:243]
	v_lshlrev_b64 v[248:249], 1, v[60:61]
	v_lshl_add_u64 v[244:245], s[94:95], 0, v[242:243]
	v_lshl_add_u64 v[246:247], s[46:47], 0, v[242:243]
	v_lshl_add_u64 v[244:245], v[244:245], 0, v[248:249]
	v_lshl_add_u64 v[246:247], v[246:247], 0, v[248:249]
	v_lshlrev_b32_e32 v128, 4, v57
	v_lshl_add_u64 v[244:245], v[244:245], 0, v[128:129]
	v_lshlrev_b32_e32 v128, 3, v57
	v_lshl_add_u64 v[246:247], v[246:247], 0, v[128:129]
	global_load_dwordx4 v[48:51], v[244:245], off
	s_mov_b32 s77, 1
	s_mov_b32 s76, 0
	s_cmp_lt_u32 s77, s39
	s_cselect_b32 s46, s48, 0
	s_cselect_b32 s47, s49, 0
	s_add_i32 s77, s77, 1
	v_lshl_add_u64 v[244:245], v[244:245], 0, s[46:47]
	global_load_dwordx4 v[52:55], v[244:245], off
	s_cmp_lt_u32 s77, s39
	s_cselect_b32 s46, s48, 0
	s_cselect_b32 s47, s49, 0
	s_add_i32 s77, s77, 1
	v_lshl_add_u64 v[244:245], v[244:245], 0, s[46:47]
	global_load_dwordx4 v[56:59], v[244:245], off
	s_cmp_lt_u32 s77, s39
	s_cselect_b32 s46, s48, 0
	s_cselect_b32 s47, s49, 0
	s_add_i32 s77, s77, 1
	v_lshl_add_u64 v[244:245], v[244:245], 0, s[46:47]
	global_load_dwordx4 v[248:251], v[244:245], off
	v_mov_b32_e32 v174, v135
	v_mov_b32_e32 v252, v150
	v_mov_b32_e32 v175, v101
	s_waitcnt vmcnt(0)
	v_mfma_f32_32x32x16_bf16 v[0:15], v[48:51], v[110:113], 0
	v_mfma_f32_32x32x16_bf16 v[16:31], v[48:51], v[102:105], 0
	v_mfma_f32_32x32x16_bf16 v[32:47], v[48:51], v[106:109], 0
	v_mfma_f32_32x32x16_bf16 v[192:207], v[48:51], v[94:97], 0
	s_nop 15
	v_permlane32_swap_b32 v0, v16
	v_permlane32_swap_b32 v1, v17
	v_permlane32_swap_b32 v2, v18
	v_permlane32_swap_b32 v3, v19
	v_permlane32_swap_b32 v4, v20
	v_permlane32_swap_b32 v5, v21
	v_permlane32_swap_b32 v6, v22
	v_permlane32_swap_b32 v7, v23
	v_permlane32_swap_b32 v8, v24
	v_permlane32_swap_b32 v9, v25
	v_permlane32_swap_b32 v10, v26
	v_permlane32_swap_b32 v11, v27
	v_permlane32_swap_b32 v12, v28
	v_permlane32_swap_b32 v13, v29
	v_permlane32_swap_b32 v14, v30
	v_permlane32_swap_b32 v15, v31
	v_permlane32_swap_b32 v32, v192
	v_permlane32_swap_b32 v33, v193
	v_permlane32_swap_b32 v34, v194
	v_permlane32_swap_b32 v35, v195
	v_permlane32_swap_b32 v36, v196
	v_permlane32_swap_b32 v37, v197
	v_permlane32_swap_b32 v38, v198
	v_permlane32_swap_b32 v39, v199
	v_permlane32_swap_b32 v40, v200
	v_permlane32_swap_b32 v41, v201
	v_permlane32_swap_b32 v42, v202
	v_permlane32_swap_b32 v43, v203
	v_permlane32_swap_b32 v44, v204
	v_permlane32_swap_b32 v45, v205
	v_permlane32_swap_b32 v46, v206
	v_permlane32_swap_b32 v47, v207
	s_nop 1

.Lscr_noy:
	v_fma_f32 v15, -v131, v204, v15
	v_fma_f32 v47, v131, v28, v47
	v_fmac_f32_e32 v15, v252, v28
	v_fmac_f32_e32 v47, v252, v204
	v_cvt_pk_bf16_f32 v98, v15, v47
	ds_write_b32 v240, v98 offset:15536
	v_fma_f32 v14, -v131, v47, v14
	v_fma_f32 v46, v131, v15, v46
	v_fmac_f32_e32 v14, v252, v15
	v_fmac_f32_e32 v46, v252, v47
	v_cvt_pk_bf16_f32 v99, v14, v46
	ds_write_b32 v240, v99 offset:15264
	v_fma_f32 v13, -v131, v46, v13
	v_fma_f32 v45, v131, v14, v45
	v_fmac_f32_e32 v13, v252, v14
	v_fmac_f32_e32 v45, v252, v46
	v_cvt_pk_bf16_f32 v98, v13, v45
	ds_write_b32 v240, v98 offset:14992
	v_fma_f32 v12, -v131, v45, v12
	v_fma_f32 v44, v131, v13, v44
	v_fmac_f32_e32 v12, v252, v13
	v_fmac_f32_e32 v44, v252, v45
	v_cvt_pk_bf16_f32 v99, v12, v44
	ds_write_b32 v240, v99 offset:14720
	v_fma_f32 v27, -v131, v44, v27
	v_fma_f32 v203, v131, v12, v203
	v_fmac_f32_e32 v27, v252, v12
	v_fmac_f32_e32 v203, v252, v44
	v_cvt_pk_bf16_f32 v98, v27, v203
	ds_write_b32 v240, v98 offset:14448
	v_fma_f32 v26, -v131, v203, v26
	v_fma_f32 v202, v131, v27, v202
	v_fmac_f32_e32 v26, v252, v27
	v_fmac_f32_e32 v202, v252, v203
	v_cvt_pk_bf16_f32 v99, v26, v202
	ds_write_b32 v240, v99 offset:14176
	v_fma_f32 v25, -v131, v202, v25
	v_fma_f32 v201, v131, v26, v201
	v_fmac_f32_e32 v25, v252, v26
	v_fmac_f32_e32 v201, v252, v202
	v_cvt_pk_bf16_f32 v98, v25, v201
	ds_write_b32 v240, v98 offset:13904
	v_fma_f32 v24, -v131, v201, v24
	v_fma_f32 v200, v131, v25, v200
	v_fmac_f32_e32 v24, v252, v25
	v_fmac_f32_e32 v200, v252, v201
	v_cvt_pk_bf16_f32 v99, v24, v200
	ds_write_b32 v240, v99 offset:13632
	v_fma_f32 v11, -v131, v200, v11
	v_fma_f32 v43, v131, v24, v43
	v_fmac_f32_e32 v11, v252, v24
	v_fmac_f32_e32 v43, v252, v200
	v_cvt_pk_bf16_f32 v98, v11, v43
	ds_write_b32 v240, v98 offset:13360
	v_fma_f32 v10, -v131, v43, v10
	v_fma_f32 v42, v131, v11, v42
	v_fmac_f32_e32 v10, v252, v11
	v_fmac_f32_e32 v42, v252, v43
	v_cvt_pk_bf16_f32 v99, v10, v42
	ds_write_b32 v240, v99 offset:13088
	v_fma_f32 v9, -v131, v42, v9
	v_fma_f32 v41, v131, v10, v41
	v_fmac_f32_e32 v9, v252, v10
	v_fmac_f32_e32 v41, v252, v42
	v_cvt_pk_bf16_f32 v98, v9, v41
	ds_write_b32 v240, v98 offset:12816
	v_fma_f32 v8, -v131, v41, v8
	v_fma_f32 v40, v131, v9, v40
	v_fmac_f32_e32 v8, v252, v9
	v_fmac_f32_e32 v40, v252, v41
	v_cvt_pk_bf16_f32 v99, v8, v40
	ds_write_b32 v240, v99 offset:12544
	v_fma_f32 v23, -v131, v40, v23
	v_fma_f32 v199, v131, v8, v199
	v_fmac_f32_e32 v23, v252, v8
	v_fmac_f32_e32 v199, v252, v40
	v_cvt_pk_bf16_f32 v98, v23, v199
	ds_write_b32 v240, v98 offset:12272
	v_fma_f32 v22, -v131, v199, v22
	v_fma_f32 v198, v131, v23, v198
	v_fmac_f32_e32 v22, v252, v23
	v_fmac_f32_e32 v198, v252, v199
	v_cvt_pk_bf16_f32 v99, v22, v198
	ds_write_b32 v240, v99 offset:12000
	v_fma_f32 v21, -v131, v198, v21
	v_fma_f32 v197, v131, v22, v197
	v_fmac_f32_e32 v21, v252, v22
	v_fmac_f32_e32 v197, v252, v198
	v_cvt_pk_bf16_f32 v98, v21, v197
	ds_write_b32 v240, v98 offset:11728
	v_fma_f32 v20, -v131, v197, v20
	v_fma_f32 v196, v131, v21, v196
	v_fmac_f32_e32 v20, v252, v21
	v_fmac_f32_e32 v196, v252, v197
	v_cvt_pk_bf16_f32 v99, v20, v196
	ds_write_b32 v240, v99 offset:11456
	v_fma_f32 v7, -v131, v196, v7
	v_fma_f32 v39, v131, v20, v39
	v_fmac_f32_e32 v7, v252, v20
	v_fmac_f32_e32 v39, v252, v196
	v_cvt_pk_bf16_f32 v98, v7, v39
	ds_write_b32 v240, v98 offset:11184
	v_fma_f32 v6, -v131, v39, v6
	v_fma_f32 v38, v131, v7, v38
	v_fmac_f32_e32 v6, v252, v7
	v_fmac_f32_e32 v38, v252, v39
	v_cvt_pk_bf16_f32 v99, v6, v38
	ds_write_b32 v240, v99 offset:10912
	v_fma_f32 v5, -v131, v38, v5
	v_fma_f32 v37, v131, v6, v37
	v_fmac_f32_e32 v5, v252, v6
	v_fmac_f32_e32 v37, v252, v38
	v_cvt_pk_bf16_f32 v98, v5, v37
	ds_write_b32 v240, v98 offset:10640
	v_fma_f32 v4, -v131, v37, v4
	v_fma_f32 v36, v131, v5, v36
	v_fmac_f32_e32 v4, v252, v5
	v_fmac_f32_e32 v36, v252, v37
	v_cvt_pk_bf16_f32 v99, v4, v36
	ds_write_b32 v240, v99 offset:10368
	v_fma_f32 v19, -v131, v36, v19
	v_fma_f32 v195, v131, v4, v195
	v_fmac_f32_e32 v19, v252, v4
	v_fmac_f32_e32 v195, v252, v36
	v_cvt_pk_bf16_f32 v98, v19, v195
	ds_write_b32 v240, v98 offset:10096
	v_fma_f32 v18, -v131, v195, v18
	v_fma_f32 v194, v131, v19, v194
	v_fmac_f32_e32 v18, v252, v19
	v_fmac_f32_e32 v194, v252, v195
	v_cvt_pk_bf16_f32 v99, v18, v194
	ds_write_b32 v240, v99 offset:9824
	v_fma_f32 v17, -v131, v194, v17
	v_fma_f32 v193, v131, v18, v193
	v_fmac_f32_e32 v17, v252, v18
	v_fmac_f32_e32 v193, v252, v194
	v_cvt_pk_bf16_f32 v98, v17, v193
	ds_write_b32 v240, v98 offset:9552
	v_fma_f32 v16, -v131, v193, v16
	v_fma_f32 v192, v131, v17, v192
	v_fmac_f32_e32 v16, v252, v17
	v_fmac_f32_e32 v192, v252, v193
	v_cvt_pk_bf16_f32 v99, v16, v192
	ds_write_b32 v240, v99 offset:9280
	v_fma_f32 v3, -v131, v192, v3
	v_fma_f32 v35, v131, v16, v35
	v_fmac_f32_e32 v3, v252, v16
	v_fmac_f32_e32 v35, v252, v192
	v_cvt_pk_bf16_f32 v98, v3, v35
	ds_write_b32 v240, v98 offset:9008
	v_fma_f32 v2, -v131, v35, v2
	v_fma_f32 v34, v131, v3, v34
	v_fmac_f32_e32 v2, v252, v3
	v_fmac_f32_e32 v34, v252, v35
	v_cvt_pk_bf16_f32 v99, v2, v34
	ds_write_b32 v240, v99 offset:8736
	v_fma_f32 v1, -v131, v34, v1
	v_fma_f32 v33, v131, v2, v33
	v_fmac_f32_e32 v1, v252, v2
	v_fmac_f32_e32 v33, v252, v34
	v_cvt_pk_bf16_f32 v98, v1, v33
	ds_write_b32 v240, v98 offset:8464
	v_fma_f32 v174, -v131, v33, v0
	v_fma_f32 v175, v131, v1, v32
	v_fmac_f32_e32 v174, v252, v1
	v_fmac_f32_e32 v175, v252, v33
	v_cvt_pk_bf16_f32 v99, v174, v175
	ds_write_b32 v240, v99 offset:8192
	s_waitcnt vmcnt(8)
	s_cmp_lt_u32 s77, s39
	s_cselect_b32 s46, s48, 0
	s_cselect_b32 s47, s49, 0
	s_add_i32 s77, s77, 1
	v_lshl_add_u64 v[244:245], v[244:245], 0, s[46:47]
	global_load_dwordx4 v[48:51], v[244:245], off
	v_mfma_f32_32x32x16_bf16 v[0:15], v[52:55], v[110:113], 0
	v_mfma_f32_32x32x16_bf16 v[16:31], v[52:55], v[102:105], 0
	v_mfma_f32_32x32x16_bf16 v[32:47], v[52:55], v[106:109], 0
	v_mfma_f32_32x32x16_bf16 v[192:207], v[52:55], v[94:97], 0
	ds_read_b128 v[208:211], v241 offset:8192
	ds_read_b128 v[212:215], v241 offset:8224
	ds_read_b128 v[216:219], v241 offset:8256
	ds_read_b128 v[220:223], v241 offset:8288
	ds_read_b128 v[224:227], v241 offset:8320
	ds_read_b128 v[228:231], v241 offset:8352
	ds_read_b128 v[232:235], v241 offset:8384
	ds_read_b128 v[236:239], v241 offset:8416
	s_waitcnt lgkmcnt(7)
	v_mfma_f32_32x32x16_bf16 v[142:157], v[90:93], v[208:211], 0
	v_permlane32_swap_b32 v0, v16
	v_permlane32_swap_b32 v1, v17
	v_permlane32_swap_b32 v2, v18
	v_permlane32_swap_b32 v3, v19
	s_waitcnt lgkmcnt(6)
	v_mfma_f32_32x32x16_bf16 v[158:173], v[86:89], v[212:215], 0
	v_permlane32_swap_b32 v4, v20
	v_permlane32_swap_b32 v5, v21
	v_permlane32_swap_b32 v6, v22
	v_permlane32_swap_b32 v7, v23
	s_waitcnt lgkmcnt(5)
	v_mfma_f32_32x32x16_bf16 v[142:157], v[82:85], v[216:219], v[142:157]
	v_permlane32_swap_b32 v8, v24
	v_permlane32_swap_b32 v9, v25
	v_permlane32_swap_b32 v10, v26
	v_permlane32_swap_b32 v11, v27
	s_waitcnt lgkmcnt(4)
	v_mfma_f32_32x32x16_bf16 v[158:173], v[78:81], v[220:223], v[158:173]
	v_permlane32_swap_b32 v12, v28
	v_permlane32_swap_b32 v13, v29
	v_permlane32_swap_b32 v14, v30
	v_permlane32_swap_b32 v15, v31
	s_waitcnt lgkmcnt(3)
	v_mfma_f32_32x32x16_bf16 v[142:157], v[74:77], v[224:227], v[142:157]
	v_permlane32_swap_b32 v32, v192
	v_permlane32_swap_b32 v33, v193
	v_permlane32_swap_b32 v34, v194
	v_permlane32_swap_b32 v35, v195
	s_waitcnt lgkmcnt(2)
	v_mfma_f32_32x32x16_bf16 v[158:173], v[70:73], v[228:231], v[158:173]
	v_permlane32_swap_b32 v36, v196
	v_permlane32_swap_b32 v37, v197
	v_permlane32_swap_b32 v38, v198
	v_permlane32_swap_b32 v39, v199
	s_waitcnt lgkmcnt(1)
	v_mfma_f32_32x32x16_bf16 v[142:157], v[66:69], v[232:235], v[142:157]
	v_permlane32_swap_b32 v40, v200
	v_permlane32_swap_b32 v41, v201
	v_permlane32_swap_b32 v42, v202
	v_permlane32_swap_b32 v43, v203
	s_waitcnt lgkmcnt(0)
	v_mfma_f32_32x32x16_bf16 v[158:173], v[62:65], v[236:239], v[158:173]
	v_permlane32_swap_b32 v44, v204
	v_permlane32_swap_b32 v45, v205
	v_permlane32_swap_b32 v46, v206
	v_permlane32_swap_b32 v47, v207
	s_nop 1
	v_fma_f32 v31, -v131, v175, v31
	v_fma_f32 v207, v131, v174, v207
	v_fmac_f32_e32 v31, v252, v174
	v_fmac_f32_e32 v207, v252, v175
	v_cvt_pk_bf16_f32 v98, v31, v207
	ds_write_b32 v240, v98 offset:16624
	v_fma_f32 v30, -v131, v207, v30
	v_fma_f32 v206, v131, v31, v206
	v_fmac_f32_e32 v30, v252, v31
	v_fmac_f32_e32 v206, v252, v207
	v_cvt_pk_bf16_f32 v99, v30, v206
	ds_write_b32 v240, v99 offset:16352
	v_fma_f32 v29, -v131, v206, v29
	v_fma_f32 v205, v131, v30, v205
	v_fmac_f32_e32 v29, v252, v30
	v_fmac_f32_e32 v205, v252, v206
	v_cvt_pk_bf16_f32 v98, v29, v205
	ds_write_b32 v240, v98 offset:16080
	v_fma_f32 v28, -v131, v205, v28
	v_fma_f32 v204, v131, v29, v204
	v_fmac_f32_e32 v28, v252, v29
	v_fmac_f32_e32 v204, v252, v205
	v_cvt_pk_bf16_f32 v99, v28, v204
	ds_write_b32 v240, v99 offset:15808
	v_add_f32_e32 v242, v142, v158
	v_add_f32_e32 v243, v143, v159
	v_add_f32_e32 v60, v144, v160
	v_add_f32_e32 v61, v145, v161
	v_add_f32_e32 v116, v146, v162
	v_add_f32_e32 v117, v147, v163
	v_add_f32_e32 v100, v148, v164
	v_add_f32_e32 v128, v149, v165
	v_cvt_pk_bf16_f32 v242, v242, v243
	v_cvt_pk_bf16_f32 v243, v60, v61
	v_cvt_pk_bf16_f32 v60, v116, v117
	v_cvt_pk_bf16_f32 v61, v100, v128
	global_store_dwordx2 v[246:247], v[242:243], off
	global_store_dwordx2 v[246:247], v[60:61], off offset:16
	v_lshl_add_u64 v[246:247], v[246:247], 0, s[48:49]
	v_fma_f32 v15, -v131, v204, v15
	v_fma_f32 v47, v131, v28, v47
	v_fmac_f32_e32 v15, v252, v28
	v_fmac_f32_e32 v47, v252, v204
	v_cvt_pk_bf16_f32 v98, v15, v47
	ds_write_b32 v240, v98 offset:15536
	v_fma_f32 v14, -v131, v47, v14
	v_fma_f32 v46, v131, v15, v46
	v_fmac_f32_e32 v14, v252, v15
	v_fmac_f32_e32 v46, v252, v47
	v_cvt_pk_bf16_f32 v99, v14, v46
	ds_write_b32 v240, v99 offset:15264
	v_fma_f32 v13, -v131, v46, v13
	v_fma_f32 v45, v131, v14, v45
	v_fmac_f32_e32 v13, v252, v14
	v_fmac_f32_e32 v45, v252, v46
	v_cvt_pk_bf16_f32 v98, v13, v45
	ds_write_b32 v240, v98 offset:14992
	v_fma_f32 v12, -v131, v45, v12
	v_fma_f32 v44, v131, v13, v44
	v_fmac_f32_e32 v12, v252, v13
	v_fmac_f32_e32 v44, v252, v45
	v_cvt_pk_bf16_f32 v99, v12, v44
	ds_write_b32 v240, v99 offset:14720
	v_fma_f32 v27, -v131, v44, v27
	v_fma_f32 v203, v131, v12, v203
	v_fmac_f32_e32 v27, v252, v12
	v_fmac_f32_e32 v203, v252, v44
	v_cvt_pk_bf16_f32 v98, v27, v203
	ds_write_b32 v240, v98 offset:14448
	v_fma_f32 v26, -v131, v203, v26
	v_fma_f32 v202, v131, v27, v202
	v_fmac_f32_e32 v26, v252, v27
	v_fmac_f32_e32 v202, v252, v203
	v_cvt_pk_bf16_f32 v99, v26, v202
	ds_write_b32 v240, v99 offset:14176
	v_fma_f32 v25, -v131, v202, v25
	v_fma_f32 v201, v131, v26, v201
	v_fmac_f32_e32 v25, v252, v26
	v_fmac_f32_e32 v201, v252, v202
	v_cvt_pk_bf16_f32 v98, v25, v201
	ds_write_b32 v240, v98 offset:13904
	v_fma_f32 v24, -v131, v201, v24
	v_fma_f32 v200, v131, v25, v200
	v_fmac_f32_e32 v24, v252, v25
	v_fmac_f32_e32 v200, v252, v201
	v_cvt_pk_bf16_f32 v99, v24, v200
	ds_write_b32 v240, v99 offset:13632
	v_fma_f32 v11, -v131, v200, v11
	v_fma_f32 v43, v131, v24, v43
	v_fmac_f32_e32 v11, v252, v24
	v_fmac_f32_e32 v43, v252, v200
	v_cvt_pk_bf16_f32 v98, v11, v43
	ds_write_b32 v240, v98 offset:13360
	v_fma_f32 v10, -v131, v43, v10
	v_fma_f32 v42, v131, v11, v42
	v_fmac_f32_e32 v10, v252, v11
	v_fmac_f32_e32 v42, v252, v43
	v_cvt_pk_bf16_f32 v99, v10, v42
	ds_write_b32 v240, v99 offset:13088
	v_fma_f32 v9, -v131, v42, v9
	v_fma_f32 v41, v131, v10, v41
	v_fmac_f32_e32 v9, v252, v10
	v_fmac_f32_e32 v41, v252, v42
	v_cvt_pk_bf16_f32 v98, v9, v41
	ds_write_b32 v240, v98 offset:12816
	v_fma_f32 v8, -v131, v41, v8
	v_fma_f32 v40, v131, v9, v40
	v_fmac_f32_e32 v8, v252, v9
	v_fmac_f32_e32 v40, v252, v41
	v_cvt_pk_bf16_f32 v99, v8, v40
	ds_write_b32 v240, v99 offset:12544
	v_fma_f32 v23, -v131, v40, v23
	v_fma_f32 v199, v131, v8, v199
	v_fmac_f32_e32 v23, v252, v8
	v_fmac_f32_e32 v199, v252, v40
	v_cvt_pk_bf16_f32 v98, v23, v199
	ds_write_b32 v240, v98 offset:12272
	v_fma_f32 v22, -v131, v199, v22
	v_fma_f32 v198, v131, v23, v198
	v_fmac_f32_e32 v22, v252, v23
	v_fmac_f32_e32 v198, v252, v199
	v_cvt_pk_bf16_f32 v99, v22, v198
	ds_write_b32 v240, v99 offset:12000
	v_fma_f32 v21, -v131, v198, v21
	v_fma_f32 v197, v131, v22, v197
	v_fmac_f32_e32 v21, v252, v22
	v_fmac_f32_e32 v197, v252, v198
	v_cvt_pk_bf16_f32 v98, v21, v197
	ds_write_b32 v240, v98 offset:11728
	v_fma_f32 v20, -v131, v197, v20
	v_fma_f32 v196, v131, v21, v196
	v_fmac_f32_e32 v20, v252, v21
	v_fmac_f32_e32 v196, v252, v197
	v_cvt_pk_bf16_f32 v99, v20, v196
	ds_write_b32 v240, v99 offset:11456
	v_fma_f32 v7, -v131, v196, v7
	v_fma_f32 v39, v131, v20, v39
	v_fmac_f32_e32 v7, v252, v20
	v_fmac_f32_e32 v39, v252, v196
	v_cvt_pk_bf16_f32 v98, v7, v39
	ds_write_b32 v240, v98 offset:11184
	v_fma_f32 v6, -v131, v39, v6
	v_fma_f32 v38, v131, v7, v38
	v_fmac_f32_e32 v6, v252, v7
	v_fmac_f32_e32 v38, v252, v39
	v_cvt_pk_bf16_f32 v99, v6, v38
	ds_write_b32 v240, v99 offset:10912
	v_fma_f32 v5, -v131, v38, v5
	v_fma_f32 v37, v131, v6, v37
	v_fmac_f32_e32 v5, v252, v6
	v_fmac_f32_e32 v37, v252, v38
	v_cvt_pk_bf16_f32 v98, v5, v37
	ds_write_b32 v240, v98 offset:10640
	v_fma_f32 v4, -v131, v37, v4
	v_fma_f32 v36, v131, v5, v36
	v_fmac_f32_e32 v4, v252, v5
	v_fmac_f32_e32 v36, v252, v37
	v_cvt_pk_bf16_f32 v99, v4, v36
	ds_write_b32 v240, v99 offset:10368
	v_fma_f32 v19, -v131, v36, v19
	v_fma_f32 v195, v131, v4, v195
	v_fmac_f32_e32 v19, v252, v4
	v_fmac_f32_e32 v195, v252, v36
	v_cvt_pk_bf16_f32 v98, v19, v195
	ds_write_b32 v240, v98 offset:10096
	v_fma_f32 v18, -v131, v195, v18
	v_fma_f32 v194, v131, v19, v194
	v_fmac_f32_e32 v18, v252, v19
	v_fmac_f32_e32 v194, v252, v195
	v_cvt_pk_bf16_f32 v99, v18, v194
	ds_write_b32 v240, v99 offset:9824
	v_fma_f32 v17, -v131, v194, v17
	v_fma_f32 v193, v131, v18, v193
	v_fmac_f32_e32 v17, v252, v18
	v_fmac_f32_e32 v193, v252, v194
	v_cvt_pk_bf16_f32 v98, v17, v193
	ds_write_b32 v240, v98 offset:9552
	v_fma_f32 v16, -v131, v193, v16
	v_fma_f32 v192, v131, v17, v192
	v_fmac_f32_e32 v16, v252, v17
	v_fmac_f32_e32 v192, v252, v193
	v_cvt_pk_bf16_f32 v99, v16, v192
	ds_write_b32 v240, v99 offset:9280
	v_fma_f32 v3, -v131, v192, v3
	v_fma_f32 v35, v131, v16, v35
	v_fmac_f32_e32 v3, v252, v16
	v_fmac_f32_e32 v35, v252, v192
	v_cvt_pk_bf16_f32 v98, v3, v35
	ds_write_b32 v240, v98 offset:9008
	v_fma_f32 v2, -v131, v35, v2
	v_fma_f32 v34, v131, v3, v34
	v_fmac_f32_e32 v2, v252, v3
	v_fmac_f32_e32 v34, v252, v35
	v_cvt_pk_bf16_f32 v99, v2, v34
	ds_write_b32 v240, v99 offset:8736
	v_fma_f32 v1, -v131, v34, v1
	v_fma_f32 v33, v131, v2, v33
	v_fmac_f32_e32 v1, v252, v2
	v_fmac_f32_e32 v33, v252, v34
	v_cvt_pk_bf16_f32 v98, v1, v33
	ds_write_b32 v240, v98 offset:8464
	v_fma_f32 v174, -v131, v33, v0
	v_fma_f32 v175, v131, v1, v32
	v_fmac_f32_e32 v174, v252, v1
	v_fmac_f32_e32 v175, v252, v33
	v_cvt_pk_bf16_f32 v99, v174, v175
	ds_write_b32 v240, v99 offset:8192
	s_waitcnt vmcnt(8)
	s_cmp_lt_u32 s77, s39
	s_cselect_b32 s46, s48, 0
	s_cselect_b32 s47, s49, 0
	s_add_i32 s77, s77, 1
	v_lshl_add_u64 v[244:245], v[244:245], 0, s[46:47]
	global_load_dwordx4 v[52:55], v[244:245], off
	v_mfma_f32_32x32x16_bf16 v[0:15], v[56:59], v[110:113], 0
	v_mfma_f32_32x32x16_bf16 v[16:31], v[56:59], v[102:105], 0
	v_mfma_f32_32x32x16_bf16 v[32:47], v[56:59], v[106:109], 0
	v_mfma_f32_32x32x16_bf16 v[192:207], v[56:59], v[94:97], 0
	ds_read_b128 v[208:211], v241 offset:8192
	ds_read_b128 v[212:215], v241 offset:8224
	ds_read_b128 v[216:219], v241 offset:8256
	ds_read_b128 v[220:223], v241 offset:8288
	ds_read_b128 v[224:227], v241 offset:8320
	ds_read_b128 v[228:231], v241 offset:8352
	ds_read_b128 v[232:235], v241 offset:8384
	ds_read_b128 v[236:239], v241 offset:8416
	s_waitcnt lgkmcnt(7)
	v_mfma_f32_32x32x16_bf16 v[142:157], v[90:93], v[208:211], 0
	v_permlane32_swap_b32 v0, v16
	v_permlane32_swap_b32 v1, v17
	v_permlane32_swap_b32 v2, v18
	v_permlane32_swap_b32 v3, v19
	s_waitcnt lgkmcnt(6)
	v_mfma_f32_32x32x16_bf16 v[158:173], v[86:89], v[212:215], 0
	v_permlane32_swap_b32 v4, v20
	v_permlane32_swap_b32 v5, v21
	v_permlane32_swap_b32 v6, v22
	v_permlane32_swap_b32 v7, v23
	s_waitcnt lgkmcnt(5)
	v_mfma_f32_32x32x16_bf16 v[142:157], v[82:85], v[216:219], v[142:157]
	v_permlane32_swap_b32 v8, v24
	v_permlane32_swap_b32 v9, v25
	v_permlane32_swap_b32 v10, v26
	v_permlane32_swap_b32 v11, v27
	s_waitcnt lgkmcnt(4)
	v_mfma_f32_32x32x16_bf16 v[158:173], v[78:81], v[220:223], v[158:173]
	v_permlane32_swap_b32 v12, v28
	v_permlane32_swap_b32 v13, v29
	v_permlane32_swap_b32 v14, v30
	v_permlane32_swap_b32 v15, v31
	s_waitcnt lgkmcnt(3)
	v_mfma_f32_32x32x16_bf16 v[142:157], v[74:77], v[224:227], v[142:157]
	v_permlane32_swap_b32 v32, v192
	v_permlane32_swap_b32 v33, v193
	v_permlane32_swap_b32 v34, v194
	v_permlane32_swap_b32 v35, v195
	s_waitcnt lgkmcnt(2)
	v_mfma_f32_32x32x16_bf16 v[158:173], v[70:73], v[228:231], v[158:173]
	v_permlane32_swap_b32 v36, v196
	v_permlane32_swap_b32 v37, v197
	v_permlane32_swap_b32 v38, v198
	v_permlane32_swap_b32 v39, v199
	s_waitcnt lgkmcnt(1)
	v_mfma_f32_32x32x16_bf16 v[142:157], v[66:69], v[232:235], v[142:157]
	v_permlane32_swap_b32 v40, v200
	v_permlane32_swap_b32 v41, v201
	v_permlane32_swap_b32 v42, v202
	v_permlane32_swap_b32 v43, v203
	s_waitcnt lgkmcnt(0)
	v_mfma_f32_32x32x16_bf16 v[158:173], v[62:65], v[236:239], v[158:173]
	v_permlane32_swap_b32 v44, v204
	v_permlane32_swap_b32 v45, v205
	v_permlane32_swap_b32 v46, v206
	v_permlane32_swap_b32 v47, v207
	s_nop 1
	v_fma_f32 v31, -v131, v175, v31
	v_fma_f32 v207, v131, v174, v207
	v_fmac_f32_e32 v31, v252, v174
	v_fmac_f32_e32 v207, v252, v175
	v_cvt_pk_bf16_f32 v98, v31, v207
	ds_write_b32 v240, v98 offset:16624
	v_fma_f32 v30, -v131, v207, v30
	v_fma_f32 v206, v131, v31, v206
	v_fmac_f32_e32 v30, v252, v31
	v_fmac_f32_e32 v206, v252, v207
	v_cvt_pk_bf16_f32 v99, v30, v206
	ds_write_b32 v240, v99 offset:16352
	v_fma_f32 v29, -v131, v206, v29
	v_fma_f32 v205, v131, v30, v205
	v_fmac_f32_e32 v29, v252, v30
	v_fmac_f32_e32 v205, v252, v206
	v_cvt_pk_bf16_f32 v98, v29, v205
	ds_write_b32 v240, v98 offset:16080
	v_fma_f32 v28, -v131, v205, v28
	v_fma_f32 v204, v131, v29, v204
	v_fmac_f32_e32 v28, v252, v29
	v_fmac_f32_e32 v204, v252, v205
	v_cvt_pk_bf16_f32 v99, v28, v204
	ds_write_b32 v240, v99 offset:15808
	v_add_f32_e32 v242, v142, v158
	v_add_f32_e32 v243, v143, v159
	v_add_f32_e32 v60, v144, v160
	v_add_f32_e32 v61, v145, v161
	v_add_f32_e32 v116, v146, v162
	v_add_f32_e32 v117, v147, v163
	v_add_f32_e32 v100, v148, v164
	v_add_f32_e32 v128, v149, v165
	v_cvt_pk_bf16_f32 v242, v242, v243
	v_cvt_pk_bf16_f32 v243, v60, v61
	v_cvt_pk_bf16_f32 v60, v116, v117
	v_cvt_pk_bf16_f32 v61, v100, v128
	global_store_dwordx2 v[246:247], v[242:243], off
	global_store_dwordx2 v[246:247], v[60:61], off offset:16
	v_lshl_add_u64 v[246:247], v[246:247], 0, s[48:49]
	v_fma_f32 v15, -v131, v204, v15
	v_fma_f32 v47, v131, v28, v47
	v_fmac_f32_e32 v15, v252, v28
	v_fmac_f32_e32 v47, v252, v204
	v_cvt_pk_bf16_f32 v98, v15, v47
	ds_write_b32 v240, v98 offset:15536
	v_fma_f32 v14, -v131, v47, v14
	v_fma_f32 v46, v131, v15, v46
	v_fmac_f32_e32 v14, v252, v15
	v_fmac_f32_e32 v46, v252, v47
	v_cvt_pk_bf16_f32 v99, v14, v46
	ds_write_b32 v240, v99 offset:15264
	v_fma_f32 v13, -v131, v46, v13
	v_fma_f32 v45, v131, v14, v45
	v_fmac_f32_e32 v13, v252, v14
	v_fmac_f32_e32 v45, v252, v46
	v_cvt_pk_bf16_f32 v98, v13, v45
	ds_write_b32 v240, v98 offset:14992
	v_fma_f32 v12, -v131, v45, v12
	v_fma_f32 v44, v131, v13, v44
	v_fmac_f32_e32 v12, v252, v13
	v_fmac_f32_e32 v44, v252, v45
	v_cvt_pk_bf16_f32 v99, v12, v44
	ds_write_b32 v240, v99 offset:14720
	v_fma_f32 v27, -v131, v44, v27
	v_fma_f32 v203, v131, v12, v203
	v_fmac_f32_e32 v27, v252, v12
	v_fmac_f32_e32 v203, v252, v44
	v_cvt_pk_bf16_f32 v98, v27, v203
	ds_write_b32 v240, v98 offset:14448
	v_fma_f32 v26, -v131, v203, v26
	v_fma_f32 v202, v131, v27, v202
	v_fmac_f32_e32 v26, v252, v27
	v_fmac_f32_e32 v202, v252, v203
	v_cvt_pk_bf16_f32 v99, v26, v202
	ds_write_b32 v240, v99 offset:14176
	v_fma_f32 v25, -v131, v202, v25
	v_fma_f32 v201, v131, v26, v201
	v_fmac_f32_e32 v25, v252, v26
	v_fmac_f32_e32 v201, v252, v202
	v_cvt_pk_bf16_f32 v98, v25, v201
	ds_write_b32 v240, v98 offset:13904
	v_fma_f32 v24, -v131, v201, v24
	v_fma_f32 v200, v131, v25, v200
	v_fmac_f32_e32 v24, v252, v25
	v_fmac_f32_e32 v200, v252, v201
	v_cvt_pk_bf16_f32 v99, v24, v200
	ds_write_b32 v240, v99 offset:13632
	v_fma_f32 v11, -v131, v200, v11
	v_fma_f32 v43, v131, v24, v43
	v_fmac_f32_e32 v11, v252, v24
	v_fmac_f32_e32 v43, v252, v200
	v_cvt_pk_bf16_f32 v98, v11, v43
	ds_write_b32 v240, v98 offset:13360
	v_fma_f32 v10, -v131, v43, v10
	v_fma_f32 v42, v131, v11, v42
	v_fmac_f32_e32 v10, v252, v11
	v_fmac_f32_e32 v42, v252, v43
	v_cvt_pk_bf16_f32 v99, v10, v42
	ds_write_b32 v240, v99 offset:13088
	v_fma_f32 v9, -v131, v42, v9
	v_fma_f32 v41, v131, v10, v41
	v_fmac_f32_e32 v9, v252, v10
	v_fmac_f32_e32 v41, v252, v42
	v_cvt_pk_bf16_f32 v98, v9, v41
	ds_write_b32 v240, v98 offset:12816
	v_fma_f32 v8, -v131, v41, v8
	v_fma_f32 v40, v131, v9, v40
	v_fmac_f32_e32 v8, v252, v9
	v_fmac_f32_e32 v40, v252, v41
	v_cvt_pk_bf16_f32 v99, v8, v40
	ds_write_b32 v240, v99 offset:12544
	v_fma_f32 v23, -v131, v40, v23
	v_fma_f32 v199, v131, v8, v199
	v_fmac_f32_e32 v23, v252, v8
	v_fmac_f32_e32 v199, v252, v40
	v_cvt_pk_bf16_f32 v98, v23, v199
	ds_write_b32 v240, v98 offset:12272
	v_fma_f32 v22, -v131, v199, v22
	v_fma_f32 v198, v131, v23, v198
	v_fmac_f32_e32 v22, v252, v23
	v_fmac_f32_e32 v198, v252, v199
	v_cvt_pk_bf16_f32 v99, v22, v198
	ds_write_b32 v240, v99 offset:12000
	v_fma_f32 v21, -v131, v198, v21
	v_fma_f32 v197, v131, v22, v197
	v_fmac_f32_e32 v21, v252, v22
	v_fmac_f32_e32 v197, v252, v198
	v_cvt_pk_bf16_f32 v98, v21, v197
	ds_write_b32 v240, v98 offset:11728
	v_fma_f32 v20, -v131, v197, v20
	v_fma_f32 v196, v131, v21, v196
	v_fmac_f32_e32 v20, v252, v21
	v_fmac_f32_e32 v196, v252, v197
	v_cvt_pk_bf16_f32 v99, v20, v196
	ds_write_b32 v240, v99 offset:11456
	v_fma_f32 v7, -v131, v196, v7
	v_fma_f32 v39, v131, v20, v39
	v_fmac_f32_e32 v7, v252, v20
	v_fmac_f32_e32 v39, v252, v196
	v_cvt_pk_bf16_f32 v98, v7, v39
	ds_write_b32 v240, v98 offset:11184
	v_fma_f32 v6, -v131, v39, v6
	v_fma_f32 v38, v131, v7, v38
	v_fmac_f32_e32 v6, v252, v7
	v_fmac_f32_e32 v38, v252, v39
	v_cvt_pk_bf16_f32 v99, v6, v38
	ds_write_b32 v240, v99 offset:10912
	v_fma_f32 v5, -v131, v38, v5
	v_fma_f32 v37, v131, v6, v37
	v_fmac_f32_e32 v5, v252, v6
	v_fmac_f32_e32 v37, v252, v38
	v_cvt_pk_bf16_f32 v98, v5, v37
	ds_write_b32 v240, v98 offset:10640
	v_fma_f32 v4, -v131, v37, v4
	v_fma_f32 v36, v131, v5, v36
	v_fmac_f32_e32 v4, v252, v5
	v_fmac_f32_e32 v36, v252, v37
	v_cvt_pk_bf16_f32 v99, v4, v36
	ds_write_b32 v240, v99 offset:10368
	v_fma_f32 v19, -v131, v36, v19
	v_fma_f32 v195, v131, v4, v195
	v_fmac_f32_e32 v19, v252, v4
	v_fmac_f32_e32 v195, v252, v36
	v_cvt_pk_bf16_f32 v98, v19, v195
	ds_write_b32 v240, v98 offset:10096
	v_fma_f32 v18, -v131, v195, v18
	v_fma_f32 v194, v131, v19, v194
	v_fmac_f32_e32 v18, v252, v19
	v_fmac_f32_e32 v194, v252, v195
	v_cvt_pk_bf16_f32 v99, v18, v194
	ds_write_b32 v240, v99 offset:9824
	v_fma_f32 v17, -v131, v194, v17
	v_fma_f32 v193, v131, v18, v193
	v_fmac_f32_e32 v17, v252, v18
	v_fmac_f32_e32 v193, v252, v194
	v_cvt_pk_bf16_f32 v98, v17, v193
	ds_write_b32 v240, v98 offset:9552
	v_fma_f32 v16, -v131, v193, v16
	v_fma_f32 v192, v131, v17, v192
	v_fmac_f32_e32 v16, v252, v17
	v_fmac_f32_e32 v192, v252, v193
	v_cvt_pk_bf16_f32 v99, v16, v192
	ds_write_b32 v240, v99 offset:9280
	v_fma_f32 v3, -v131, v192, v3
	v_fma_f32 v35, v131, v16, v35
	v_fmac_f32_e32 v3, v252, v16
	v_fmac_f32_e32 v35, v252, v192
	v_cvt_pk_bf16_f32 v98, v3, v35
	ds_write_b32 v240, v98 offset:9008
	v_fma_f32 v2, -v131, v35, v2
	v_fma_f32 v34, v131, v3, v34
	v_fmac_f32_e32 v2, v252, v3
	v_fmac_f32_e32 v34, v252, v35
	v_cvt_pk_bf16_f32 v99, v2, v34
	ds_write_b32 v240, v99 offset:8736
	v_fma_f32 v1, -v131, v34, v1
	v_fma_f32 v33, v131, v2, v33
	v_fmac_f32_e32 v1, v252, v2
	v_fmac_f32_e32 v33, v252, v34
	v_cvt_pk_bf16_f32 v98, v1, v33
	ds_write_b32 v240, v98 offset:8464
	v_fma_f32 v174, -v131, v33, v0
	v_fma_f32 v175, v131, v1, v32
	v_fmac_f32_e32 v174, v252, v1
	v_fmac_f32_e32 v175, v252, v33
	v_cvt_pk_bf16_f32 v99, v174, v175
	ds_write_b32 v240, v99 offset:8192
	s_waitcnt vmcnt(8)
	s_cmp_lt_u32 s77, s39
	s_cselect_b32 s46, s48, 0
	s_cselect_b32 s47, s49, 0
	s_add_i32 s77, s77, 1
	v_lshl_add_u64 v[244:245], v[244:245], 0, s[46:47]
	global_load_dwordx4 v[56:59], v[244:245], off
	v_mfma_f32_32x32x16_bf16 v[0:15], v[248:251], v[110:113], 0
	v_mfma_f32_32x32x16_bf16 v[16:31], v[248:251], v[102:105], 0
	v_mfma_f32_32x32x16_bf16 v[32:47], v[248:251], v[106:109], 0
	v_mfma_f32_32x32x16_bf16 v[192:207], v[248:251], v[94:97], 0
	ds_read_b128 v[208:211], v241 offset:8192
	ds_read_b128 v[212:215], v241 offset:8224
	ds_read_b128 v[216:219], v241 offset:8256
	ds_read_b128 v[220:223], v241 offset:8288
	ds_read_b128 v[224:227], v241 offset:8320
	ds_read_b128 v[228:231], v241 offset:8352
	ds_read_b128 v[232:235], v241 offset:8384
	ds_read_b128 v[236:239], v241 offset:8416
	s_waitcnt lgkmcnt(7)
	v_mfma_f32_32x32x16_bf16 v[142:157], v[90:93], v[208:211], 0
	v_permlane32_swap_b32 v0, v16
	v_permlane32_swap_b32 v1, v17
	v_permlane32_swap_b32 v2, v18
	v_permlane32_swap_b32 v3, v19
	s_waitcnt lgkmcnt(6)
	v_mfma_f32_32x32x16_bf16 v[158:173], v[86:89], v[212:215], 0
	v_permlane32_swap_b32 v4, v20
	v_permlane32_swap_b32 v5, v21
	v_permlane32_swap_b32 v6, v22
	v_permlane32_swap_b32 v7, v23
	s_waitcnt lgkmcnt(5)
	v_mfma_f32_32x32x16_bf16 v[142:157], v[82:85], v[216:219], v[142:157]
	v_permlane32_swap_b32 v8, v24
	v_permlane32_swap_b32 v9, v25
	v_permlane32_swap_b32 v10, v26
	v_permlane32_swap_b32 v11, v27
	s_waitcnt lgkmcnt(4)
	v_mfma_f32_32x32x16_bf16 v[158:173], v[78:81], v[220:223], v[158:173]
	v_permlane32_swap_b32 v12, v28
	v_permlane32_swap_b32 v13, v29
	v_permlane32_swap_b32 v14, v30
	v_permlane32_swap_b32 v15, v31
	s_waitcnt lgkmcnt(3)
	v_mfma_f32_32x32x16_bf16 v[142:157], v[74:77], v[224:227], v[142:157]
	v_permlane32_swap_b32 v32, v192
	v_permlane32_swap_b32 v33, v193
	v_permlane32_swap_b32 v34, v194
	v_permlane32_swap_b32 v35, v195
	s_waitcnt lgkmcnt(2)
	v_mfma_f32_32x32x16_bf16 v[158:173], v[70:73], v[228:231], v[158:173]
	v_permlane32_swap_b32 v36, v196
	v_permlane32_swap_b32 v37, v197
	v_permlane32_swap_b32 v38, v198
	v_permlane32_swap_b32 v39, v199
	s_waitcnt lgkmcnt(1)
	v_mfma_f32_32x32x16_bf16 v[142:157], v[66:69], v[232:235], v[142:157]
	v_permlane32_swap_b32 v40, v200
	v_permlane32_swap_b32 v41, v201
	v_permlane32_swap_b32 v42, v202
	v_permlane32_swap_b32 v43, v203
	s_waitcnt lgkmcnt(0)
	v_mfma_f32_32x32x16_bf16 v[158:173], v[62:65], v[236:239], v[158:173]
	v_permlane32_swap_b32 v44, v204
	v_permlane32_swap_b32 v45, v205
	v_permlane32_swap_b32 v46, v206
	v_permlane32_swap_b32 v47, v207
	s_nop 1
	v_fma_f32 v31, -v131, v175, v31
	v_fma_f32 v207, v131, v174, v207
	v_fmac_f32_e32 v31, v252, v174
	v_fmac_f32_e32 v207, v252, v175
	v_cvt_pk_bf16_f32 v98, v31, v207
	ds_write_b32 v240, v98 offset:16624
	v_fma_f32 v30, -v131, v207, v30
	v_fma_f32 v206, v131, v31, v206
	v_fmac_f32_e32 v30, v252, v31
	v_fmac_f32_e32 v206, v252, v207
	v_cvt_pk_bf16_f32 v99, v30, v206
	ds_write_b32 v240, v99 offset:16352
	v_fma_f32 v29, -v131, v206, v29
	v_fma_f32 v205, v131, v30, v205
	v_fmac_f32_e32 v29, v252, v30
	v_fmac_f32_e32 v205, v252, v206
	v_cvt_pk_bf16_f32 v98, v29, v205
	ds_write_b32 v240, v98 offset:16080
	v_fma_f32 v28, -v131, v205, v28
	v_fma_f32 v204, v131, v29, v204
	v_fmac_f32_e32 v28, v252, v29
	v_fmac_f32_e32 v204, v252, v205
	v_cvt_pk_bf16_f32 v99, v28, v204
	ds_write_b32 v240, v99 offset:15808
	v_add_f32_e32 v242, v142, v158
	v_add_f32_e32 v243, v143, v159
	v_add_f32_e32 v60, v144, v160
	v_add_f32_e32 v61, v145, v161
	v_add_f32_e32 v116, v146, v162
	v_add_f32_e32 v117, v147, v163
	v_add_f32_e32 v100, v148, v164
	v_add_f32_e32 v128, v149, v165
	v_cvt_pk_bf16_f32 v242, v242, v243
	v_cvt_pk_bf16_f32 v243, v60, v61
	v_cvt_pk_bf16_f32 v60, v116, v117
	v_cvt_pk_bf16_f32 v61, v100, v128
	global_store_dwordx2 v[246:247], v[242:243], off
	global_store_dwordx2 v[246:247], v[60:61], off offset:16
	v_lshl_add_u64 v[246:247], v[246:247], 0, s[48:49]
	v_fma_f32 v15, -v131, v204, v15
	v_fma_f32 v47, v131, v28, v47
	v_fmac_f32_e32 v15, v252, v28
	v_fmac_f32_e32 v47, v252, v204
	v_cvt_pk_bf16_f32 v98, v15, v47
	ds_write_b32 v240, v98 offset:15536
	v_fma_f32 v14, -v131, v47, v14
	v_fma_f32 v46, v131, v15, v46
	v_fmac_f32_e32 v14, v252, v15
	v_fmac_f32_e32 v46, v252, v47
	v_cvt_pk_bf16_f32 v99, v14, v46
	ds_write_b32 v240, v99 offset:15264
	v_fma_f32 v13, -v131, v46, v13
	v_fma_f32 v45, v131, v14, v45
	v_fmac_f32_e32 v13, v252, v14
	v_fmac_f32_e32 v45, v252, v46
	v_cvt_pk_bf16_f32 v98, v13, v45
	ds_write_b32 v240, v98 offset:14992
	v_fma_f32 v12, -v131, v45, v12
	v_fma_f32 v44, v131, v13, v44
	v_fmac_f32_e32 v12, v252, v13
	v_fmac_f32_e32 v44, v252, v45
	v_cvt_pk_bf16_f32 v99, v12, v44
	ds_write_b32 v240, v99 offset:14720
	v_fma_f32 v27, -v131, v44, v27
	v_fma_f32 v203, v131, v12, v203
	v_fmac_f32_e32 v27, v252, v12
	v_fmac_f32_e32 v203, v252, v44
	v_cvt_pk_bf16_f32 v98, v27, v203
	ds_write_b32 v240, v98 offset:14448
	v_fma_f32 v26, -v131, v203, v26
	v_fma_f32 v202, v131, v27, v202
	v_fmac_f32_e32 v26, v252, v27
	v_fmac_f32_e32 v202, v252, v203
	v_cvt_pk_bf16_f32 v99, v26, v202
	ds_write_b32 v240, v99 offset:14176
	v_fma_f32 v25, -v131, v202, v25
	v_fma_f32 v201, v131, v26, v201
	v_fmac_f32_e32 v25, v252, v26
	v_fmac_f32_e32 v201, v252, v202
	v_cvt_pk_bf16_f32 v98, v25, v201
	ds_write_b32 v240, v98 offset:13904
	v_fma_f32 v24, -v131, v201, v24
	v_fma_f32 v200, v131, v25, v200
	v_fmac_f32_e32 v24, v252, v25
	v_fmac_f32_e32 v200, v252, v201
	v_cvt_pk_bf16_f32 v99, v24, v200
	ds_write_b32 v240, v99 offset:13632
	v_fma_f32 v11, -v131, v200, v11
	v_fma_f32 v43, v131, v24, v43
	v_fmac_f32_e32 v11, v252, v24
	v_fmac_f32_e32 v43, v252, v200
	v_cvt_pk_bf16_f32 v98, v11, v43
	ds_write_b32 v240, v98 offset:13360
	v_fma_f32 v10, -v131, v43, v10
	v_fma_f32 v42, v131, v11, v42
	v_fmac_f32_e32 v10, v252, v11
	v_fmac_f32_e32 v42, v252, v43
	v_cvt_pk_bf16_f32 v99, v10, v42
	ds_write_b32 v240, v99 offset:13088
	v_fma_f32 v9, -v131, v42, v9
	v_fma_f32 v41, v131, v10, v41
	v_fmac_f32_e32 v9, v252, v10
	v_fmac_f32_e32 v41, v252, v42
	v_cvt_pk_bf16_f32 v98, v9, v41
	ds_write_b32 v240, v98 offset:12816
	v_fma_f32 v8, -v131, v41, v8
	v_fma_f32 v40, v131, v9, v40
	v_fmac_f32_e32 v8, v252, v9
	v_fmac_f32_e32 v40, v252, v41
	v_cvt_pk_bf16_f32 v99, v8, v40
	ds_write_b32 v240, v99 offset:12544
	v_fma_f32 v23, -v131, v40, v23
	v_fma_f32 v199, v131, v8, v199
	v_fmac_f32_e32 v23, v252, v8
	v_fmac_f32_e32 v199, v252, v40
	v_cvt_pk_bf16_f32 v98, v23, v199
	ds_write_b32 v240, v98 offset:12272
	v_fma_f32 v22, -v131, v199, v22
	v_fma_f32 v198, v131, v23, v198
	v_fmac_f32_e32 v22, v252, v23
	v_fmac_f32_e32 v198, v252, v199
	v_cvt_pk_bf16_f32 v99, v22, v198
	ds_write_b32 v240, v99 offset:12000
	v_fma_f32 v21, -v131, v198, v21
	v_fma_f32 v197, v131, v22, v197
	v_fmac_f32_e32 v21, v252, v22
	v_fmac_f32_e32 v197, v252, v198
	v_cvt_pk_bf16_f32 v98, v21, v197
	ds_write_b32 v240, v98 offset:11728
	v_fma_f32 v20, -v131, v197, v20
	v_fma_f32 v196, v131, v21, v196
	v_fmac_f32_e32 v20, v252, v21
	v_fmac_f32_e32 v196, v252, v197
	v_cvt_pk_bf16_f32 v99, v20, v196
	ds_write_b32 v240, v99 offset:11456
	v_fma_f32 v7, -v131, v196, v7
	v_fma_f32 v39, v131, v20, v39
	v_fmac_f32_e32 v7, v252, v20
	v_fmac_f32_e32 v39, v252, v196
	v_cvt_pk_bf16_f32 v98, v7, v39
	ds_write_b32 v240, v98 offset:11184
	v_fma_f32 v6, -v131, v39, v6
	v_fma_f32 v38, v131, v7, v38
	v_fmac_f32_e32 v6, v252, v7
	v_fmac_f32_e32 v38, v252, v39
	v_cvt_pk_bf16_f32 v99, v6, v38
	ds_write_b32 v240, v99 offset:10912
	v_fma_f32 v5, -v131, v38, v5
	v_fma_f32 v37, v131, v6, v37
	v_fmac_f32_e32 v5, v252, v6
	v_fmac_f32_e32 v37, v252, v38
	v_cvt_pk_bf16_f32 v98, v5, v37
	ds_write_b32 v240, v98 offset:10640
	v_fma_f32 v4, -v131, v37, v4
	v_fma_f32 v36, v131, v5, v36
	v_fmac_f32_e32 v4, v252, v5
	v_fmac_f32_e32 v36, v252, v37
	v_cvt_pk_bf16_f32 v99, v4, v36
	ds_write_b32 v240, v99 offset:10368
	v_fma_f32 v19, -v131, v36, v19
	v_fma_f32 v195, v131, v4, v195
	v_fmac_f32_e32 v19, v252, v4
	v_fmac_f32_e32 v195, v252, v36
	v_cvt_pk_bf16_f32 v98, v19, v195
	ds_write_b32 v240, v98 offset:10096
	v_fma_f32 v18, -v131, v195, v18
	v_fma_f32 v194, v131, v19, v194
	v_fmac_f32_e32 v18, v252, v19
	v_fmac_f32_e32 v194, v252, v195
	v_cvt_pk_bf16_f32 v99, v18, v194
	ds_write_b32 v240, v99 offset:9824
	v_fma_f32 v17, -v131, v194, v17
	v_fma_f32 v193, v131, v18, v193
	v_fmac_f32_e32 v17, v252, v18
	v_fmac_f32_e32 v193, v252, v194
	v_cvt_pk_bf16_f32 v98, v17, v193
	ds_write_b32 v240, v98 offset:9552
	v_fma_f32 v16, -v131, v193, v16
	v_fma_f32 v192, v131, v17, v192
	v_fmac_f32_e32 v16, v252, v17
	v_fmac_f32_e32 v192, v252, v193
	v_cvt_pk_bf16_f32 v99, v16, v192
	ds_write_b32 v240, v99 offset:9280
	v_fma_f32 v3, -v131, v192, v3
	v_fma_f32 v35, v131, v16, v35
	v_fmac_f32_e32 v3, v252, v16
	v_fmac_f32_e32 v35, v252, v192
	v_cvt_pk_bf16_f32 v98, v3, v35
	ds_write_b32 v240, v98 offset:9008
	v_fma_f32 v2, -v131, v35, v2
	v_fma_f32 v34, v131, v3, v34
	v_fmac_f32_e32 v2, v252, v3
	v_fmac_f32_e32 v34, v252, v35
	v_cvt_pk_bf16_f32 v99, v2, v34
	ds_write_b32 v240, v99 offset:8736
	v_fma_f32 v1, -v131, v34, v1
	v_fma_f32 v33, v131, v2, v33
	v_fmac_f32_e32 v1, v252, v2
	v_fmac_f32_e32 v33, v252, v34
	v_cvt_pk_bf16_f32 v98, v1, v33
	ds_write_b32 v240, v98 offset:8464
	v_fma_f32 v174, -v131, v33, v0
	v_fma_f32 v175, v131, v1, v32
	v_fmac_f32_e32 v174, v252, v1
	v_fmac_f32_e32 v175, v252, v33
	v_cvt_pk_bf16_f32 v99, v174, v175
	ds_write_b32 v240, v99 offset:8192
	s_waitcnt vmcnt(8)
	s_cmp_lt_u32 s77, s39
	s_cselect_b32 s46, s48, 0
	s_cselect_b32 s47, s49, 0
	s_add_i32 s77, s77, 1
	v_lshl_add_u64 v[244:245], v[244:245], 0, s[46:47]
	global_load_dwordx4 v[248:251], v[244:245], off
	v_mfma_f32_32x32x16_bf16 v[0:15], v[48:51], v[110:113], 0
	v_mfma_f32_32x32x16_bf16 v[16:31], v[48:51], v[102:105], 0
	v_mfma_f32_32x32x16_bf16 v[32:47], v[48:51], v[106:109], 0
	v_mfma_f32_32x32x16_bf16 v[192:207], v[48:51], v[94:97], 0
	ds_read_b128 v[208:211], v241 offset:8192
	ds_read_b128 v[212:215], v241 offset:8224
	ds_read_b128 v[216:219], v241 offset:8256
	ds_read_b128 v[220:223], v241 offset:8288
	ds_read_b128 v[224:227], v241 offset:8320
	ds_read_b128 v[228:231], v241 offset:8352
	ds_read_b128 v[232:235], v241 offset:8384
	ds_read_b128 v[236:239], v241 offset:8416
	s_waitcnt lgkmcnt(7)
	v_mfma_f32_32x32x16_bf16 v[142:157], v[90:93], v[208:211], 0
	v_permlane32_swap_b32 v0, v16
	v_permlane32_swap_b32 v1, v17
	v_permlane32_swap_b32 v2, v18
	v_permlane32_swap_b32 v3, v19
	s_waitcnt lgkmcnt(6)
	v_mfma_f32_32x32x16_bf16 v[158:173], v[86:89], v[212:215], 0
	v_permlane32_swap_b32 v4, v20
	v_permlane32_swap_b32 v5, v21
	v_permlane32_swap_b32 v6, v22
	v_permlane32_swap_b32 v7, v23
	s_waitcnt lgkmcnt(5)
	v_mfma_f32_32x32x16_bf16 v[142:157], v[82:85], v[216:219], v[142:157]
	v_permlane32_swap_b32 v8, v24
	v_permlane32_swap_b32 v9, v25
	v_permlane32_swap_b32 v10, v26
	v_permlane32_swap_b32 v11, v27
	s_waitcnt lgkmcnt(4)
	v_mfma_f32_32x32x16_bf16 v[158:173], v[78:81], v[220:223], v[158:173]
	v_permlane32_swap_b32 v12, v28
	v_permlane32_swap_b32 v13, v29
	v_permlane32_swap_b32 v14, v30
	v_permlane32_swap_b32 v15, v31
	s_waitcnt lgkmcnt(3)
	v_mfma_f32_32x32x16_bf16 v[142:157], v[74:77], v[224:227], v[142:157]
	v_permlane32_swap_b32 v32, v192
	v_permlane32_swap_b32 v33, v193
	v_permlane32_swap_b32 v34, v194
	v_permlane32_swap_b32 v35, v195
	s_waitcnt lgkmcnt(2)
	v_mfma_f32_32x32x16_bf16 v[158:173], v[70:73], v[228:231], v[158:173]
	v_permlane32_swap_b32 v36, v196
	v_permlane32_swap_b32 v37, v197
	v_permlane32_swap_b32 v38, v198
	v_permlane32_swap_b32 v39, v199
	s_waitcnt lgkmcnt(1)
	v_mfma_f32_32x32x16_bf16 v[142:157], v[66:69], v[232:235], v[142:157]
	v_permlane32_swap_b32 v40, v200
	v_permlane32_swap_b32 v41, v201
	v_permlane32_swap_b32 v42, v202
	v_permlane32_swap_b32 v43, v203
	s_waitcnt lgkmcnt(0)
	v_mfma_f32_32x32x16_bf16 v[158:173], v[62:65], v[236:239], v[158:173]
	v_permlane32_swap_b32 v44, v204
	v_permlane32_swap_b32 v45, v205
	v_permlane32_swap_b32 v46, v206
	v_permlane32_swap_b32 v47, v207
	s_add_i32 s76, s76, 4
	s_cmp_lt_u32 s76, s39
	s_cbranch_scc1 .Lscr_loop
	s_nop 15
	v_add_f32_e32 v242, v142, v158
	v_add_f32_e32 v243, v143, v159
	v_add_f32_e32 v60, v144, v160
	v_add_f32_e32 v61, v145, v161
	v_add_f32_e32 v116, v146, v162
	v_add_f32_e32 v117, v147, v163
	v_add_f32_e32 v100, v148, v164
	v_add_f32_e32 v128, v149, v165
	v_cvt_pk_bf16_f32 v242, v242, v243
	v_cvt_pk_bf16_f32 v243, v60, v61
	v_cvt_pk_bf16_f32 v60, v116, v117
	v_cvt_pk_bf16_f32 v61, v100, v128
	global_store_dwordx2 v[246:247], v[242:243], off
	global_store_dwordx2 v[246:247], v[60:61], off offset:16
	v_lshl_add_u64 v[246:247], v[246:247], 0, s[48:49]
	v_mov_b32_e32 v114, v174
	v_mov_b32_e32 v115, v175
	s_branch .LBB0_629
.LBB0_622:
	s_and_b64 vcc, exec, s[48:49]
	s_cbranch_vccz .LBB0_630
	v_and_b32_e32 v56, 31, v133
	v_bfe_u32 v57, v133, 5, 1
	v_and_b32_e32 v58, 63, v133
	v_lshl_add_u32 v240, v58, 2, v127
	v_mul_u32_u24_e32 v59, 0x110, v56
	v_lshl_add_u32 v241, v57, 4, v127
	v_add_u32_e32 v241, v241, v59
	v_add_u32_e32 v242, s51, v56
	s_mov_b32 s48, 0x10000
	s_mov_b32 s49, 0
	v_mov_b32_e32 v243, 0
	v_lshlrev_b64 v[242:243], 11, v[242:243]
	v_lshlrev_b64 v[248:249], 1, v[60:61]
	v_lshl_add_u64 v[244:245], s[94:95], 0, v[242:243]
	v_lshl_add_u64 v[246:247], s[46:47], 0, v[242:243]
	v_lshl_add_u64 v[244:245], v[244:245], 0, v[248:249]
	v_lshl_add_u64 v[246:247], v[246:247], 0, v[248:249]
	v_lshlrev_b32_e32 v128, 4, v57
	v_lshl_add_u64 v[244:245], v[244:245], 0, v[128:129]
	v_lshlrev_b32_e32 v128, 3, v57
	v_lshl_add_u64 v[246:247], v[246:247], 0, v[128:129]
	global_load_dwordx4 v[48:51], v[244:245], off
	s_mov_b32 s77, 1
	s_mov_b32 s76, 0
	s_cmp_lt_u32 s77, s39
	s_cselect_b32 s46, s48, 0
	s_cselect_b32 s47, s49, 0
	s_add_i32 s77, s77, 1
	v_lshl_add_u64 v[244:245], v[244:245], 0, s[46:47]
	global_load_dwordx4 v[52:55], v[244:245], off
	s_cmp_lt_u32 s77, s39
	s_cselect_b32 s46, s48, 0
	s_cselect_b32 s47, s49, 0
	s_add_i32 s77, s77, 1
	v_lshl_add_u64 v[244:245], v[244:245], 0, s[46:47]
	global_load_dwordx4 v[56:59], v[244:245], off
	s_cmp_lt_u32 s77, s39
	s_cselect_b32 s46, s48, 0
	s_cselect_b32 s47, s49, 0
	s_add_i32 s77, s77, 1
	v_lshl_add_u64 v[244:245], v[244:245], 0, s[46:47]
	global_load_dwordx4 v[248:251], v[244:245], off
	v_mov_b32_e32 v174, v135
	v_mov_b32_e32 v252, v150
	v_mov_b32_e32 v175, v101
	s_waitcnt vmcnt(0)
	v_mfma_f32_32x32x16_bf16 v[0:15], v[48:51], v[110:113], 0
	v_mfma_f32_32x32x16_bf16 v[16:31], v[48:51], v[102:105], 0
	v_mfma_f32_32x32x16_bf16 v[32:47], v[48:51], v[106:109], 0
	v_mfma_f32_32x32x16_bf16 v[192:207], v[48:51], v[94:97], 0
	s_nop 15
	v_permlane32_swap_b32 v0, v16
	v_permlane32_swap_b32 v1, v17
	v_permlane32_swap_b32 v2, v18
	v_permlane32_swap_b32 v3, v19
	v_permlane32_swap_b32 v4, v20
	v_permlane32_swap_b32 v5, v21
	v_permlane32_swap_b32 v6, v22
	v_permlane32_swap_b32 v7, v23
	v_permlane32_swap_b32 v8, v24
	v_permlane32_swap_b32 v9, v25
	v_permlane32_swap_b32 v10, v26
	v_permlane32_swap_b32 v11, v27
	v_permlane32_swap_b32 v12, v28
	v_permlane32_swap_b32 v13, v29
	v_permlane32_swap_b32 v14, v30
	v_permlane32_swap_b32 v15, v31
	v_permlane32_swap_b32 v32, v192
	v_permlane32_swap_b32 v33, v193
	v_permlane32_swap_b32 v34, v194
	v_permlane32_swap_b32 v35, v195
	v_permlane32_swap_b32 v36, v196
	v_permlane32_swap_b32 v37, v197
	v_permlane32_swap_b32 v38, v198
	v_permlane32_swap_b32 v39, v199
	v_permlane32_swap_b32 v40, v200
	v_permlane32_swap_b32 v41, v201
	v_permlane32_swap_b32 v42, v202
	v_permlane32_swap_b32 v43, v203
	v_permlane32_swap_b32 v44, v204
	v_permlane32_swap_b32 v45, v205
	v_permlane32_swap_b32 v46, v206
	v_permlane32_swap_b32 v47, v207
	s_nop 1

.Lscf_noy:
	v_fma_f32 v16, -v131, v35, v16
	v_fma_f32 v192, v131, v3, v192
	v_fmac_f32_e32 v16, v252, v3
	v_fmac_f32_e32 v192, v252, v35
	v_cvt_pk_bf16_f32 v98, v16, v192
	ds_write_b32 v240, v98 offset:9280
	v_fma_f32 v17, -v131, v192, v17
	v_fma_f32 v193, v131, v16, v193
	v_fmac_f32_e32 v17, v252, v16
	v_fmac_f32_e32 v193, v252, v192
	v_cvt_pk_bf16_f32 v99, v17, v193
	ds_write_b32 v240, v99 offset:9552
	v_fma_f32 v18, -v131, v193, v18
	v_fma_f32 v194, v131, v17, v194
	v_fmac_f32_e32 v18, v252, v17
	v_fmac_f32_e32 v194, v252, v193
	v_cvt_pk_bf16_f32 v98, v18, v194
	ds_write_b32 v240, v98 offset:9824
	v_fma_f32 v19, -v131, v194, v19
	v_fma_f32 v195, v131, v18, v195
	v_fmac_f32_e32 v19, v252, v18
	v_fmac_f32_e32 v195, v252, v194
	v_cvt_pk_bf16_f32 v99, v19, v195
	ds_write_b32 v240, v99 offset:10096
	v_fma_f32 v4, -v131, v195, v4
	v_fma_f32 v36, v131, v19, v36
	v_fmac_f32_e32 v4, v252, v19
	v_fmac_f32_e32 v36, v252, v195
	v_cvt_pk_bf16_f32 v98, v4, v36
	ds_write_b32 v240, v98 offset:10368
	v_fma_f32 v5, -v131, v36, v5
	v_fma_f32 v37, v131, v4, v37
	v_fmac_f32_e32 v5, v252, v4
	v_fmac_f32_e32 v37, v252, v36
	v_cvt_pk_bf16_f32 v99, v5, v37
	ds_write_b32 v240, v99 offset:10640
	v_fma_f32 v6, -v131, v37, v6
	v_fma_f32 v38, v131, v5, v38
	v_fmac_f32_e32 v6, v252, v5
	v_fmac_f32_e32 v38, v252, v37
	v_cvt_pk_bf16_f32 v98, v6, v38
	ds_write_b32 v240, v98 offset:10912
	v_fma_f32 v7, -v131, v38, v7
	v_fma_f32 v39, v131, v6, v39
	v_fmac_f32_e32 v7, v252, v6
	v_fmac_f32_e32 v39, v252, v38
	v_cvt_pk_bf16_f32 v99, v7, v39
	ds_write_b32 v240, v99 offset:11184
	v_fma_f32 v20, -v131, v39, v20
	v_fma_f32 v196, v131, v7, v196
	v_fmac_f32_e32 v20, v252, v7
	v_fmac_f32_e32 v196, v252, v39
	v_cvt_pk_bf16_f32 v98, v20, v196
	ds_write_b32 v240, v98 offset:11456
	v_fma_f32 v21, -v131, v196, v21
	v_fma_f32 v197, v131, v20, v197
	v_fmac_f32_e32 v21, v252, v20
	v_fmac_f32_e32 v197, v252, v196
	v_cvt_pk_bf16_f32 v99, v21, v197
	ds_write_b32 v240, v99 offset:11728
	v_fma_f32 v22, -v131, v197, v22
	v_fma_f32 v198, v131, v21, v198
	v_fmac_f32_e32 v22, v252, v21
	v_fmac_f32_e32 v198, v252, v197
	v_cvt_pk_bf16_f32 v98, v22, v198
	ds_write_b32 v240, v98 offset:12000
	v_fma_f32 v23, -v131, v198, v23
	v_fma_f32 v199, v131, v22, v199
	v_fmac_f32_e32 v23, v252, v22
	v_fmac_f32_e32 v199, v252, v198
	v_cvt_pk_bf16_f32 v99, v23, v199
	ds_write_b32 v240, v99 offset:12272
	v_fma_f32 v8, -v131, v199, v8
	v_fma_f32 v40, v131, v23, v40
	v_fmac_f32_e32 v8, v252, v23
	v_fmac_f32_e32 v40, v252, v199
	v_cvt_pk_bf16_f32 v98, v8, v40
	ds_write_b32 v240, v98 offset:12544
	v_fma_f32 v9, -v131, v40, v9
	v_fma_f32 v41, v131, v8, v41
	v_fmac_f32_e32 v9, v252, v8
	v_fmac_f32_e32 v41, v252, v40
	v_cvt_pk_bf16_f32 v99, v9, v41
	ds_write_b32 v240, v99 offset:12816
	v_fma_f32 v10, -v131, v41, v10
	v_fma_f32 v42, v131, v9, v42
	v_fmac_f32_e32 v10, v252, v9
	v_fmac_f32_e32 v42, v252, v41
	v_cvt_pk_bf16_f32 v98, v10, v42
	ds_write_b32 v240, v98 offset:13088
	v_fma_f32 v11, -v131, v42, v11
	v_fma_f32 v43, v131, v10, v43
	v_fmac_f32_e32 v11, v252, v10
	v_fmac_f32_e32 v43, v252, v42
	v_cvt_pk_bf16_f32 v99, v11, v43
	ds_write_b32 v240, v99 offset:13360
	v_fma_f32 v24, -v131, v43, v24
	v_fma_f32 v200, v131, v11, v200
	v_fmac_f32_e32 v24, v252, v11
	v_fmac_f32_e32 v200, v252, v43
	v_cvt_pk_bf16_f32 v98, v24, v200
	ds_write_b32 v240, v98 offset:13632
	v_fma_f32 v25, -v131, v200, v25
	v_fma_f32 v201, v131, v24, v201
	v_fmac_f32_e32 v25, v252, v24
	v_fmac_f32_e32 v201, v252, v200
	v_cvt_pk_bf16_f32 v99, v25, v201
	ds_write_b32 v240, v99 offset:13904
	v_fma_f32 v26, -v131, v201, v26
	v_fma_f32 v202, v131, v25, v202
	v_fmac_f32_e32 v26, v252, v25
	v_fmac_f32_e32 v202, v252, v201
	v_cvt_pk_bf16_f32 v98, v26, v202
	ds_write_b32 v240, v98 offset:14176
	v_fma_f32 v27, -v131, v202, v27
	v_fma_f32 v203, v131, v26, v203
	v_fmac_f32_e32 v27, v252, v26
	v_fmac_f32_e32 v203, v252, v202
	v_cvt_pk_bf16_f32 v99, v27, v203
	ds_write_b32 v240, v99 offset:14448
	v_fma_f32 v12, -v131, v203, v12
	v_fma_f32 v44, v131, v27, v44
	v_fmac_f32_e32 v12, v252, v27
	v_fmac_f32_e32 v44, v252, v203
	v_cvt_pk_bf16_f32 v98, v12, v44
	ds_write_b32 v240, v98 offset:14720
	v_fma_f32 v13, -v131, v44, v13
	v_fma_f32 v45, v131, v12, v45
	v_fmac_f32_e32 v13, v252, v12
	v_fmac_f32_e32 v45, v252, v44
	v_cvt_pk_bf16_f32 v99, v13, v45
	ds_write_b32 v240, v99 offset:14992
	v_fma_f32 v14, -v131, v45, v14
	v_fma_f32 v46, v131, v13, v46
	v_fmac_f32_e32 v14, v252, v13
	v_fmac_f32_e32 v46, v252, v45
	v_cvt_pk_bf16_f32 v98, v14, v46
	ds_write_b32 v240, v98 offset:15264
	v_fma_f32 v15, -v131, v46, v15
	v_fma_f32 v47, v131, v14, v47
	v_fmac_f32_e32 v15, v252, v14
	v_fmac_f32_e32 v47, v252, v46
	v_cvt_pk_bf16_f32 v99, v15, v47
	ds_write_b32 v240, v99 offset:15536
	v_fma_f32 v28, -v131, v47, v28
	v_fma_f32 v204, v131, v15, v204
	v_fmac_f32_e32 v28, v252, v15
	v_fmac_f32_e32 v204, v252, v47
	v_cvt_pk_bf16_f32 v98, v28, v204
	ds_write_b32 v240, v98 offset:15808
	v_fma_f32 v29, -v131, v204, v29
	v_fma_f32 v205, v131, v28, v205
	v_fmac_f32_e32 v29, v252, v28
	v_fmac_f32_e32 v205, v252, v204
	v_cvt_pk_bf16_f32 v99, v29, v205
	ds_write_b32 v240, v99 offset:16080
	v_fma_f32 v30, -v131, v205, v30
	v_fma_f32 v206, v131, v29, v206
	v_fmac_f32_e32 v30, v252, v29
	v_fmac_f32_e32 v206, v252, v205
	v_cvt_pk_bf16_f32 v98, v30, v206
	ds_write_b32 v240, v98 offset:16352
	v_fma_f32 v174, -v131, v206, v31
	v_fma_f32 v175, v131, v30, v207
	v_fmac_f32_e32 v174, v252, v30
	v_fmac_f32_e32 v175, v252, v206
	v_cvt_pk_bf16_f32 v99, v174, v175
	ds_write_b32 v240, v99 offset:16624
	s_waitcnt vmcnt(8)
	s_cmp_lt_u32 s77, s39
	s_cselect_b32 s46, s48, 0
	s_cselect_b32 s47, s49, 0
	s_add_i32 s77, s77, 1
	v_lshl_add_u64 v[244:245], v[244:245], 0, s[46:47]
	global_load_dwordx4 v[48:51], v[244:245], off
	v_mfma_f32_32x32x16_bf16 v[0:15], v[52:55], v[110:113], 0
	v_mfma_f32_32x32x16_bf16 v[16:31], v[52:55], v[102:105], 0
	v_mfma_f32_32x32x16_bf16 v[32:47], v[52:55], v[106:109], 0
	v_mfma_f32_32x32x16_bf16 v[192:207], v[52:55], v[94:97], 0
	ds_read_b128 v[208:211], v241 offset:8192
	ds_read_b128 v[212:215], v241 offset:8224
	ds_read_b128 v[216:219], v241 offset:8256
	ds_read_b128 v[220:223], v241 offset:8288
	ds_read_b128 v[224:227], v241 offset:8320
	ds_read_b128 v[228:231], v241 offset:8352
	ds_read_b128 v[232:235], v241 offset:8384
	ds_read_b128 v[236:239], v241 offset:8416
	s_waitcnt lgkmcnt(7)
	v_mfma_f32_32x32x16_bf16 v[142:157], v[90:93], v[208:211], 0
	v_permlane32_swap_b32 v0, v16
	v_permlane32_swap_b32 v1, v17
	v_permlane32_swap_b32 v2, v18
	v_permlane32_swap_b32 v3, v19
	s_waitcnt lgkmcnt(6)
	v_mfma_f32_32x32x16_bf16 v[158:173], v[86:89], v[212:215], 0
	v_permlane32_swap_b32 v4, v20
	v_permlane32_swap_b32 v5, v21
	v_permlane32_swap_b32 v6, v22
	v_permlane32_swap_b32 v7, v23
	s_waitcnt lgkmcnt(5)
	v_mfma_f32_32x32x16_bf16 v[142:157], v[82:85], v[216:219], v[142:157]
	v_permlane32_swap_b32 v8, v24
	v_permlane32_swap_b32 v9, v25
	v_permlane32_swap_b32 v10, v26
	v_permlane32_swap_b32 v11, v27
	s_waitcnt lgkmcnt(4)
	v_mfma_f32_32x32x16_bf16 v[158:173], v[78:81], v[220:223], v[158:173]
	v_permlane32_swap_b32 v12, v28
	v_permlane32_swap_b32 v13, v29
	v_permlane32_swap_b32 v14, v30
	v_permlane32_swap_b32 v15, v31
	s_waitcnt lgkmcnt(3)
	v_mfma_f32_32x32x16_bf16 v[142:157], v[74:77], v[224:227], v[142:157]
	v_permlane32_swap_b32 v32, v192
	v_permlane32_swap_b32 v33, v193
	v_permlane32_swap_b32 v34, v194
	v_permlane32_swap_b32 v35, v195
	s_waitcnt lgkmcnt(2)
	v_mfma_f32_32x32x16_bf16 v[158:173], v[70:73], v[228:231], v[158:173]
	v_permlane32_swap_b32 v36, v196
	v_permlane32_swap_b32 v37, v197
	v_permlane32_swap_b32 v38, v198
	v_permlane32_swap_b32 v39, v199
	s_waitcnt lgkmcnt(1)
	v_mfma_f32_32x32x16_bf16 v[142:157], v[66:69], v[232:235], v[142:157]
	v_permlane32_swap_b32 v40, v200
	v_permlane32_swap_b32 v41, v201
	v_permlane32_swap_b32 v42, v202
	v_permlane32_swap_b32 v43, v203
	s_waitcnt lgkmcnt(0)
	v_mfma_f32_32x32x16_bf16 v[158:173], v[62:65], v[236:239], v[158:173]
	v_permlane32_swap_b32 v44, v204
	v_permlane32_swap_b32 v45, v205
	v_permlane32_swap_b32 v46, v206
	v_permlane32_swap_b32 v47, v207
	s_nop 1
	v_fma_f32 v0, -v131, v175, v0
	v_fma_f32 v32, v131, v174, v32
	v_fmac_f32_e32 v0, v252, v174
	v_fmac_f32_e32 v32, v252, v175
	v_cvt_pk_bf16_f32 v98, v0, v32
	ds_write_b32 v240, v98 offset:8192
	v_fma_f32 v1, -v131, v32, v1
	v_fma_f32 v33, v131, v0, v33
	v_fmac_f32_e32 v1, v252, v0
	v_fmac_f32_e32 v33, v252, v32
	v_cvt_pk_bf16_f32 v99, v1, v33
	ds_write_b32 v240, v99 offset:8464
	v_fma_f32 v2, -v131, v33, v2
	v_fma_f32 v34, v131, v1, v34
	v_fmac_f32_e32 v2, v252, v1
	v_fmac_f32_e32 v34, v252, v33
	v_cvt_pk_bf16_f32 v98, v2, v34
	ds_write_b32 v240, v98 offset:8736
	v_fma_f32 v3, -v131, v34, v3
	v_fma_f32 v35, v131, v2, v35
	v_fmac_f32_e32 v3, v252, v2
	v_fmac_f32_e32 v35, v252, v34
	v_cvt_pk_bf16_f32 v99, v3, v35
	ds_write_b32 v240, v99 offset:9008
	v_add_f32_e32 v242, v142, v158
	v_add_f32_e32 v243, v143, v159
	v_add_f32_e32 v60, v144, v160
	v_add_f32_e32 v61, v145, v161
	v_add_f32_e32 v116, v146, v162
	v_add_f32_e32 v117, v147, v163
	v_add_f32_e32 v100, v148, v164
	v_add_f32_e32 v128, v149, v165
	v_cvt_pk_bf16_f32 v242, v242, v243
	v_cvt_pk_bf16_f32 v243, v60, v61
	v_cvt_pk_bf16_f32 v60, v116, v117
	v_cvt_pk_bf16_f32 v61, v100, v128
	global_store_dwordx2 v[246:247], v[242:243], off
	global_store_dwordx2 v[246:247], v[60:61], off offset:16
	v_lshl_add_u64 v[246:247], v[246:247], 0, s[48:49]
	v_fma_f32 v16, -v131, v35, v16
	v_fma_f32 v192, v131, v3, v192
	v_fmac_f32_e32 v16, v252, v3
	v_fmac_f32_e32 v192, v252, v35
	v_cvt_pk_bf16_f32 v98, v16, v192
	ds_write_b32 v240, v98 offset:9280
	v_fma_f32 v17, -v131, v192, v17
	v_fma_f32 v193, v131, v16, v193
	v_fmac_f32_e32 v17, v252, v16
	v_fmac_f32_e32 v193, v252, v192
	v_cvt_pk_bf16_f32 v99, v17, v193
	ds_write_b32 v240, v99 offset:9552
	v_fma_f32 v18, -v131, v193, v18
	v_fma_f32 v194, v131, v17, v194
	v_fmac_f32_e32 v18, v252, v17
	v_fmac_f32_e32 v194, v252, v193
	v_cvt_pk_bf16_f32 v98, v18, v194
	ds_write_b32 v240, v98 offset:9824
	v_fma_f32 v19, -v131, v194, v19
	v_fma_f32 v195, v131, v18, v195
	v_fmac_f32_e32 v19, v252, v18
	v_fmac_f32_e32 v195, v252, v194
	v_cvt_pk_bf16_f32 v99, v19, v195
	ds_write_b32 v240, v99 offset:10096
	v_fma_f32 v4, -v131, v195, v4
	v_fma_f32 v36, v131, v19, v36
	v_fmac_f32_e32 v4, v252, v19
	v_fmac_f32_e32 v36, v252, v195
	v_cvt_pk_bf16_f32 v98, v4, v36
	ds_write_b32 v240, v98 offset:10368
	v_fma_f32 v5, -v131, v36, v5
	v_fma_f32 v37, v131, v4, v37
	v_fmac_f32_e32 v5, v252, v4
	v_fmac_f32_e32 v37, v252, v36
	v_cvt_pk_bf16_f32 v99, v5, v37
	ds_write_b32 v240, v99 offset:10640
	v_fma_f32 v6, -v131, v37, v6
	v_fma_f32 v38, v131, v5, v38
	v_fmac_f32_e32 v6, v252, v5
	v_fmac_f32_e32 v38, v252, v37
	v_cvt_pk_bf16_f32 v98, v6, v38
	ds_write_b32 v240, v98 offset:10912
	v_fma_f32 v7, -v131, v38, v7
	v_fma_f32 v39, v131, v6, v39
	v_fmac_f32_e32 v7, v252, v6
	v_fmac_f32_e32 v39, v252, v38
	v_cvt_pk_bf16_f32 v99, v7, v39
	ds_write_b32 v240, v99 offset:11184
	v_fma_f32 v20, -v131, v39, v20
	v_fma_f32 v196, v131, v7, v196
	v_fmac_f32_e32 v20, v252, v7
	v_fmac_f32_e32 v196, v252, v39
	v_cvt_pk_bf16_f32 v98, v20, v196
	ds_write_b32 v240, v98 offset:11456
	v_fma_f32 v21, -v131, v196, v21
	v_fma_f32 v197, v131, v20, v197
	v_fmac_f32_e32 v21, v252, v20
	v_fmac_f32_e32 v197, v252, v196
	v_cvt_pk_bf16_f32 v99, v21, v197
	ds_write_b32 v240, v99 offset:11728
	v_fma_f32 v22, -v131, v197, v22
	v_fma_f32 v198, v131, v21, v198
	v_fmac_f32_e32 v22, v252, v21
	v_fmac_f32_e32 v198, v252, v197
	v_cvt_pk_bf16_f32 v98, v22, v198
	ds_write_b32 v240, v98 offset:12000
	v_fma_f32 v23, -v131, v198, v23
	v_fma_f32 v199, v131, v22, v199
	v_fmac_f32_e32 v23, v252, v22
	v_fmac_f32_e32 v199, v252, v198
	v_cvt_pk_bf16_f32 v99, v23, v199
	ds_write_b32 v240, v99 offset:12272
	v_fma_f32 v8, -v131, v199, v8
	v_fma_f32 v40, v131, v23, v40
	v_fmac_f32_e32 v8, v252, v23
	v_fmac_f32_e32 v40, v252, v199
	v_cvt_pk_bf16_f32 v98, v8, v40
	ds_write_b32 v240, v98 offset:12544
	v_fma_f32 v9, -v131, v40, v9
	v_fma_f32 v41, v131, v8, v41
	v_fmac_f32_e32 v9, v252, v8
	v_fmac_f32_e32 v41, v252, v40
	v_cvt_pk_bf16_f32 v99, v9, v41
	ds_write_b32 v240, v99 offset:12816
	v_fma_f32 v10, -v131, v41, v10
	v_fma_f32 v42, v131, v9, v42
	v_fmac_f32_e32 v10, v252, v9
	v_fmac_f32_e32 v42, v252, v41
	v_cvt_pk_bf16_f32 v98, v10, v42
	ds_write_b32 v240, v98 offset:13088
	v_fma_f32 v11, -v131, v42, v11
	v_fma_f32 v43, v131, v10, v43
	v_fmac_f32_e32 v11, v252, v10
	v_fmac_f32_e32 v43, v252, v42
	v_cvt_pk_bf16_f32 v99, v11, v43
	ds_write_b32 v240, v99 offset:13360
	v_fma_f32 v24, -v131, v43, v24
	v_fma_f32 v200, v131, v11, v200
	v_fmac_f32_e32 v24, v252, v11
	v_fmac_f32_e32 v200, v252, v43
	v_cvt_pk_bf16_f32 v98, v24, v200
	ds_write_b32 v240, v98 offset:13632
	v_fma_f32 v25, -v131, v200, v25
	v_fma_f32 v201, v131, v24, v201
	v_fmac_f32_e32 v25, v252, v24
	v_fmac_f32_e32 v201, v252, v200
	v_cvt_pk_bf16_f32 v99, v25, v201
	ds_write_b32 v240, v99 offset:13904
	v_fma_f32 v26, -v131, v201, v26
	v_fma_f32 v202, v131, v25, v202
	v_fmac_f32_e32 v26, v252, v25
	v_fmac_f32_e32 v202, v252, v201
	v_cvt_pk_bf16_f32 v98, v26, v202
	ds_write_b32 v240, v98 offset:14176
	v_fma_f32 v27, -v131, v202, v27
	v_fma_f32 v203, v131, v26, v203
	v_fmac_f32_e32 v27, v252, v26
	v_fmac_f32_e32 v203, v252, v202
	v_cvt_pk_bf16_f32 v99, v27, v203
	ds_write_b32 v240, v99 offset:14448
	v_fma_f32 v12, -v131, v203, v12
	v_fma_f32 v44, v131, v27, v44
	v_fmac_f32_e32 v12, v252, v27
	v_fmac_f32_e32 v44, v252, v203
	v_cvt_pk_bf16_f32 v98, v12, v44
	ds_write_b32 v240, v98 offset:14720
	v_fma_f32 v13, -v131, v44, v13
	v_fma_f32 v45, v131, v12, v45
	v_fmac_f32_e32 v13, v252, v12
	v_fmac_f32_e32 v45, v252, v44
	v_cvt_pk_bf16_f32 v99, v13, v45
	ds_write_b32 v240, v99 offset:14992
	v_fma_f32 v14, -v131, v45, v14
	v_fma_f32 v46, v131, v13, v46
	v_fmac_f32_e32 v14, v252, v13
	v_fmac_f32_e32 v46, v252, v45
	v_cvt_pk_bf16_f32 v98, v14, v46
	ds_write_b32 v240, v98 offset:15264
	v_fma_f32 v15, -v131, v46, v15
	v_fma_f32 v47, v131, v14, v47
	v_fmac_f32_e32 v15, v252, v14
	v_fmac_f32_e32 v47, v252, v46
	v_cvt_pk_bf16_f32 v99, v15, v47
	ds_write_b32 v240, v99 offset:15536
	v_fma_f32 v28, -v131, v47, v28
	v_fma_f32 v204, v131, v15, v204
	v_fmac_f32_e32 v28, v252, v15
	v_fmac_f32_e32 v204, v252, v47
	v_cvt_pk_bf16_f32 v98, v28, v204
	ds_write_b32 v240, v98 offset:15808
	v_fma_f32 v29, -v131, v204, v29
	v_fma_f32 v205, v131, v28, v205
	v_fmac_f32_e32 v29, v252, v28
	v_fmac_f32_e32 v205, v252, v204
	v_cvt_pk_bf16_f32 v99, v29, v205
	ds_write_b32 v240, v99 offset:16080
	v_fma_f32 v30, -v131, v205, v30
	v_fma_f32 v206, v131, v29, v206
	v_fmac_f32_e32 v30, v252, v29
	v_fmac_f32_e32 v206, v252, v205
	v_cvt_pk_bf16_f32 v98, v30, v206
	ds_write_b32 v240, v98 offset:16352
	v_fma_f32 v174, -v131, v206, v31
	v_fma_f32 v175, v131, v30, v207
	v_fmac_f32_e32 v174, v252, v30
	v_fmac_f32_e32 v175, v252, v206
	v_cvt_pk_bf16_f32 v99, v174, v175
	ds_write_b32 v240, v99 offset:16624
	s_waitcnt vmcnt(8)
	s_cmp_lt_u32 s77, s39
	s_cselect_b32 s46, s48, 0
	s_cselect_b32 s47, s49, 0
	s_add_i32 s77, s77, 1
	v_lshl_add_u64 v[244:245], v[244:245], 0, s[46:47]
	global_load_dwordx4 v[52:55], v[244:245], off
	v_mfma_f32_32x32x16_bf16 v[0:15], v[56:59], v[110:113], 0
	v_mfma_f32_32x32x16_bf16 v[16:31], v[56:59], v[102:105], 0
	v_mfma_f32_32x32x16_bf16 v[32:47], v[56:59], v[106:109], 0
	v_mfma_f32_32x32x16_bf16 v[192:207], v[56:59], v[94:97], 0
	ds_read_b128 v[208:211], v241 offset:8192
	ds_read_b128 v[212:215], v241 offset:8224
	ds_read_b128 v[216:219], v241 offset:8256
	ds_read_b128 v[220:223], v241 offset:8288
	ds_read_b128 v[224:227], v241 offset:8320
	ds_read_b128 v[228:231], v241 offset:8352
	ds_read_b128 v[232:235], v241 offset:8384
	ds_read_b128 v[236:239], v241 offset:8416
	s_waitcnt lgkmcnt(7)
	v_mfma_f32_32x32x16_bf16 v[142:157], v[90:93], v[208:211], 0
	v_permlane32_swap_b32 v0, v16
	v_permlane32_swap_b32 v1, v17
	v_permlane32_swap_b32 v2, v18
	v_permlane32_swap_b32 v3, v19
	s_waitcnt lgkmcnt(6)
	v_mfma_f32_32x32x16_bf16 v[158:173], v[86:89], v[212:215], 0
	v_permlane32_swap_b32 v4, v20
	v_permlane32_swap_b32 v5, v21
	v_permlane32_swap_b32 v6, v22
	v_permlane32_swap_b32 v7, v23
	s_waitcnt lgkmcnt(5)
	v_mfma_f32_32x32x16_bf16 v[142:157], v[82:85], v[216:219], v[142:157]
	v_permlane32_swap_b32 v8, v24
	v_permlane32_swap_b32 v9, v25
	v_permlane32_swap_b32 v10, v26
	v_permlane32_swap_b32 v11, v27
	s_waitcnt lgkmcnt(4)
	v_mfma_f32_32x32x16_bf16 v[158:173], v[78:81], v[220:223], v[158:173]
	v_permlane32_swap_b32 v12, v28
	v_permlane32_swap_b32 v13, v29
	v_permlane32_swap_b32 v14, v30
	v_permlane32_swap_b32 v15, v31
	s_waitcnt lgkmcnt(3)
	v_mfma_f32_32x32x16_bf16 v[142:157], v[74:77], v[224:227], v[142:157]
	v_permlane32_swap_b32 v32, v192
	v_permlane32_swap_b32 v33, v193
	v_permlane32_swap_b32 v34, v194
	v_permlane32_swap_b32 v35, v195
	s_waitcnt lgkmcnt(2)
	v_mfma_f32_32x32x16_bf16 v[158:173], v[70:73], v[228:231], v[158:173]
	v_permlane32_swap_b32 v36, v196
	v_permlane32_swap_b32 v37, v197
	v_permlane32_swap_b32 v38, v198
	v_permlane32_swap_b32 v39, v199
	s_waitcnt lgkmcnt(1)
	v_mfma_f32_32x32x16_bf16 v[142:157], v[66:69], v[232:235], v[142:157]
	v_permlane32_swap_b32 v40, v200
	v_permlane32_swap_b32 v41, v201
	v_permlane32_swap_b32 v42, v202
	v_permlane32_swap_b32 v43, v203
	s_waitcnt lgkmcnt(0)
	v_mfma_f32_32x32x16_bf16 v[158:173], v[62:65], v[236:239], v[158:173]
	v_permlane32_swap_b32 v44, v204
	v_permlane32_swap_b32 v45, v205
	v_permlane32_swap_b32 v46, v206
	v_permlane32_swap_b32 v47, v207
	s_nop 1
	v_fma_f32 v0, -v131, v175, v0
	v_fma_f32 v32, v131, v174, v32
	v_fmac_f32_e32 v0, v252, v174
	v_fmac_f32_e32 v32, v252, v175
	v_cvt_pk_bf16_f32 v98, v0, v32
	ds_write_b32 v240, v98 offset:8192
	v_fma_f32 v1, -v131, v32, v1
	v_fma_f32 v33, v131, v0, v33
	v_fmac_f32_e32 v1, v252, v0
	v_fmac_f32_e32 v33, v252, v32
	v_cvt_pk_bf16_f32 v99, v1, v33
	ds_write_b32 v240, v99 offset:8464
	v_fma_f32 v2, -v131, v33, v2
	v_fma_f32 v34, v131, v1, v34
	v_fmac_f32_e32 v2, v252, v1
	v_fmac_f32_e32 v34, v252, v33
	v_cvt_pk_bf16_f32 v98, v2, v34
	ds_write_b32 v240, v98 offset:8736
	v_fma_f32 v3, -v131, v34, v3
	v_fma_f32 v35, v131, v2, v35
	v_fmac_f32_e32 v3, v252, v2
	v_fmac_f32_e32 v35, v252, v34
	v_cvt_pk_bf16_f32 v99, v3, v35
	ds_write_b32 v240, v99 offset:9008
	v_add_f32_e32 v242, v142, v158
	v_add_f32_e32 v243, v143, v159
	v_add_f32_e32 v60, v144, v160
	v_add_f32_e32 v61, v145, v161
	v_add_f32_e32 v116, v146, v162
	v_add_f32_e32 v117, v147, v163
	v_add_f32_e32 v100, v148, v164
	v_add_f32_e32 v128, v149, v165
	v_cvt_pk_bf16_f32 v242, v242, v243
	v_cvt_pk_bf16_f32 v243, v60, v61
	v_cvt_pk_bf16_f32 v60, v116, v117
	v_cvt_pk_bf16_f32 v61, v100, v128
	global_store_dwordx2 v[246:247], v[242:243], off
	global_store_dwordx2 v[246:247], v[60:61], off offset:16
	v_lshl_add_u64 v[246:247], v[246:247], 0, s[48:49]
	v_fma_f32 v16, -v131, v35, v16
	v_fma_f32 v192, v131, v3, v192
	v_fmac_f32_e32 v16, v252, v3
	v_fmac_f32_e32 v192, v252, v35
	v_cvt_pk_bf16_f32 v98, v16, v192
	ds_write_b32 v240, v98 offset:9280
	v_fma_f32 v17, -v131, v192, v17
	v_fma_f32 v193, v131, v16, v193
	v_fmac_f32_e32 v17, v252, v16
	v_fmac_f32_e32 v193, v252, v192
	v_cvt_pk_bf16_f32 v99, v17, v193
	ds_write_b32 v240, v99 offset:9552
	v_fma_f32 v18, -v131, v193, v18
	v_fma_f32 v194, v131, v17, v194
	v_fmac_f32_e32 v18, v252, v17
	v_fmac_f32_e32 v194, v252, v193
	v_cvt_pk_bf16_f32 v98, v18, v194
	ds_write_b32 v240, v98 offset:9824
	v_fma_f32 v19, -v131, v194, v19
	v_fma_f32 v195, v131, v18, v195
	v_fmac_f32_e32 v19, v252, v18
	v_fmac_f32_e32 v195, v252, v194
	v_cvt_pk_bf16_f32 v99, v19, v195
	ds_write_b32 v240, v99 offset:10096
	v_fma_f32 v4, -v131, v195, v4
	v_fma_f32 v36, v131, v19, v36
	v_fmac_f32_e32 v4, v252, v19
	v_fmac_f32_e32 v36, v252, v195
	v_cvt_pk_bf16_f32 v98, v4, v36
	ds_write_b32 v240, v98 offset:10368
	v_fma_f32 v5, -v131, v36, v5
	v_fma_f32 v37, v131, v4, v37
	v_fmac_f32_e32 v5, v252, v4
	v_fmac_f32_e32 v37, v252, v36
	v_cvt_pk_bf16_f32 v99, v5, v37
	ds_write_b32 v240, v99 offset:10640
	v_fma_f32 v6, -v131, v37, v6
	v_fma_f32 v38, v131, v5, v38
	v_fmac_f32_e32 v6, v252, v5
	v_fmac_f32_e32 v38, v252, v37
	v_cvt_pk_bf16_f32 v98, v6, v38
	ds_write_b32 v240, v98 offset:10912
	v_fma_f32 v7, -v131, v38, v7
	v_fma_f32 v39, v131, v6, v39
	v_fmac_f32_e32 v7, v252, v6
	v_fmac_f32_e32 v39, v252, v38
	v_cvt_pk_bf16_f32 v99, v7, v39
	ds_write_b32 v240, v99 offset:11184
	v_fma_f32 v20, -v131, v39, v20
	v_fma_f32 v196, v131, v7, v196
	v_fmac_f32_e32 v20, v252, v7
	v_fmac_f32_e32 v196, v252, v39
	v_cvt_pk_bf16_f32 v98, v20, v196
	ds_write_b32 v240, v98 offset:11456
	v_fma_f32 v21, -v131, v196, v21
	v_fma_f32 v197, v131, v20, v197
	v_fmac_f32_e32 v21, v252, v20
	v_fmac_f32_e32 v197, v252, v196
	v_cvt_pk_bf16_f32 v99, v21, v197
	ds_write_b32 v240, v99 offset:11728
	v_fma_f32 v22, -v131, v197, v22
	v_fma_f32 v198, v131, v21, v198
	v_fmac_f32_e32 v22, v252, v21
	v_fmac_f32_e32 v198, v252, v197
	v_cvt_pk_bf16_f32 v98, v22, v198
	ds_write_b32 v240, v98 offset:12000
	v_fma_f32 v23, -v131, v198, v23
	v_fma_f32 v199, v131, v22, v199
	v_fmac_f32_e32 v23, v252, v22
	v_fmac_f32_e32 v199, v252, v198
	v_cvt_pk_bf16_f32 v99, v23, v199
	ds_write_b32 v240, v99 offset:12272
	v_fma_f32 v8, -v131, v199, v8
	v_fma_f32 v40, v131, v23, v40
	v_fmac_f32_e32 v8, v252, v23
	v_fmac_f32_e32 v40, v252, v199
	v_cvt_pk_bf16_f32 v98, v8, v40
	ds_write_b32 v240, v98 offset:12544
	v_fma_f32 v9, -v131, v40, v9
	v_fma_f32 v41, v131, v8, v41
	v_fmac_f32_e32 v9, v252, v8
	v_fmac_f32_e32 v41, v252, v40
	v_cvt_pk_bf16_f32 v99, v9, v41
	ds_write_b32 v240, v99 offset:12816
	v_fma_f32 v10, -v131, v41, v10
	v_fma_f32 v42, v131, v9, v42
	v_fmac_f32_e32 v10, v252, v9
	v_fmac_f32_e32 v42, v252, v41
	v_cvt_pk_bf16_f32 v98, v10, v42
	ds_write_b32 v240, v98 offset:13088
	v_fma_f32 v11, -v131, v42, v11
	v_fma_f32 v43, v131, v10, v43
	v_fmac_f32_e32 v11, v252, v10
	v_fmac_f32_e32 v43, v252, v42
	v_cvt_pk_bf16_f32 v99, v11, v43
	ds_write_b32 v240, v99 offset:13360
	v_fma_f32 v24, -v131, v43, v24
	v_fma_f32 v200, v131, v11, v200
	v_fmac_f32_e32 v24, v252, v11
	v_fmac_f32_e32 v200, v252, v43
	v_cvt_pk_bf16_f32 v98, v24, v200
	ds_write_b32 v240, v98 offset:13632
	v_fma_f32 v25, -v131, v200, v25
	v_fma_f32 v201, v131, v24, v201
	v_fmac_f32_e32 v25, v252, v24
	v_fmac_f32_e32 v201, v252, v200
	v_cvt_pk_bf16_f32 v99, v25, v201
	ds_write_b32 v240, v99 offset:13904
	v_fma_f32 v26, -v131, v201, v26
	v_fma_f32 v202, v131, v25, v202
	v_fmac_f32_e32 v26, v252, v25
	v_fmac_f32_e32 v202, v252, v201
	v_cvt_pk_bf16_f32 v98, v26, v202
	ds_write_b32 v240, v98 offset:14176
	v_fma_f32 v27, -v131, v202, v27
	v_fma_f32 v203, v131, v26, v203
	v_fmac_f32_e32 v27, v252, v26
	v_fmac_f32_e32 v203, v252, v202
	v_cvt_pk_bf16_f32 v99, v27, v203
	ds_write_b32 v240, v99 offset:14448
	v_fma_f32 v12, -v131, v203, v12
	v_fma_f32 v44, v131, v27, v44
	v_fmac_f32_e32 v12, v252, v27
	v_fmac_f32_e32 v44, v252, v203
	v_cvt_pk_bf16_f32 v98, v12, v44
	ds_write_b32 v240, v98 offset:14720
	v_fma_f32 v13, -v131, v44, v13
	v_fma_f32 v45, v131, v12, v45
	v_fmac_f32_e32 v13, v252, v12
	v_fmac_f32_e32 v45, v252, v44
	v_cvt_pk_bf16_f32 v99, v13, v45
	ds_write_b32 v240, v99 offset:14992
	v_fma_f32 v14, -v131, v45, v14
	v_fma_f32 v46, v131, v13, v46
	v_fmac_f32_e32 v14, v252, v13
	v_fmac_f32_e32 v46, v252, v45
	v_cvt_pk_bf16_f32 v98, v14, v46
	ds_write_b32 v240, v98 offset:15264
	v_fma_f32 v15, -v131, v46, v15
	v_fma_f32 v47, v131, v14, v47
	v_fmac_f32_e32 v15, v252, v14
	v_fmac_f32_e32 v47, v252, v46
	v_cvt_pk_bf16_f32 v99, v15, v47
	ds_write_b32 v240, v99 offset:15536
	v_fma_f32 v28, -v131, v47, v28
	v_fma_f32 v204, v131, v15, v204
	v_fmac_f32_e32 v28, v252, v15
	v_fmac_f32_e32 v204, v252, v47
	v_cvt_pk_bf16_f32 v98, v28, v204
	ds_write_b32 v240, v98 offset:15808
	v_fma_f32 v29, -v131, v204, v29
	v_fma_f32 v205, v131, v28, v205
	v_fmac_f32_e32 v29, v252, v28
	v_fmac_f32_e32 v205, v252, v204
	v_cvt_pk_bf16_f32 v99, v29, v205
	ds_write_b32 v240, v99 offset:16080
	v_fma_f32 v30, -v131, v205, v30
	v_fma_f32 v206, v131, v29, v206
	v_fmac_f32_e32 v30, v252, v29
	v_fmac_f32_e32 v206, v252, v205
	v_cvt_pk_bf16_f32 v98, v30, v206
	ds_write_b32 v240, v98 offset:16352
	v_fma_f32 v174, -v131, v206, v31
	v_fma_f32 v175, v131, v30, v207
	v_fmac_f32_e32 v174, v252, v30
	v_fmac_f32_e32 v175, v252, v206
	v_cvt_pk_bf16_f32 v99, v174, v175
	ds_write_b32 v240, v99 offset:16624
	s_waitcnt vmcnt(8)
	s_cmp_lt_u32 s77, s39
	s_cselect_b32 s46, s48, 0
	s_cselect_b32 s47, s49, 0
	s_add_i32 s77, s77, 1
	v_lshl_add_u64 v[244:245], v[244:245], 0, s[46:47]
	global_load_dwordx4 v[56:59], v[244:245], off
	v_mfma_f32_32x32x16_bf16 v[0:15], v[248:251], v[110:113], 0
	v_mfma_f32_32x32x16_bf16 v[16:31], v[248:251], v[102:105], 0
	v_mfma_f32_32x32x16_bf16 v[32:47], v[248:251], v[106:109], 0
	v_mfma_f32_32x32x16_bf16 v[192:207], v[248:251], v[94:97], 0
	ds_read_b128 v[208:211], v241 offset:8192
	ds_read_b128 v[212:215], v241 offset:8224
	ds_read_b128 v[216:219], v241 offset:8256
	ds_read_b128 v[220:223], v241 offset:8288
	ds_read_b128 v[224:227], v241 offset:8320
	ds_read_b128 v[228:231], v241 offset:8352
	ds_read_b128 v[232:235], v241 offset:8384
	ds_read_b128 v[236:239], v241 offset:8416
	s_waitcnt lgkmcnt(7)
	v_mfma_f32_32x32x16_bf16 v[142:157], v[90:93], v[208:211], 0
	v_permlane32_swap_b32 v0, v16
	v_permlane32_swap_b32 v1, v17
	v_permlane32_swap_b32 v2, v18
	v_permlane32_swap_b32 v3, v19
	s_waitcnt lgkmcnt(6)
	v_mfma_f32_32x32x16_bf16 v[158:173], v[86:89], v[212:215], 0
	v_permlane32_swap_b32 v4, v20
	v_permlane32_swap_b32 v5, v21
	v_permlane32_swap_b32 v6, v22
	v_permlane32_swap_b32 v7, v23
	s_waitcnt lgkmcnt(5)
	v_mfma_f32_32x32x16_bf16 v[142:157], v[82:85], v[216:219], v[142:157]
	v_permlane32_swap_b32 v8, v24
	v_permlane32_swap_b32 v9, v25
	v_permlane32_swap_b32 v10, v26
	v_permlane32_swap_b32 v11, v27
	s_waitcnt lgkmcnt(4)
	v_mfma_f32_32x32x16_bf16 v[158:173], v[78:81], v[220:223], v[158:173]
	v_permlane32_swap_b32 v12, v28
	v_permlane32_swap_b32 v13, v29
	v_permlane32_swap_b32 v14, v30
	v_permlane32_swap_b32 v15, v31
	s_waitcnt lgkmcnt(3)
	v_mfma_f32_32x32x16_bf16 v[142:157], v[74:77], v[224:227], v[142:157]
	v_permlane32_swap_b32 v32, v192
	v_permlane32_swap_b32 v33, v193
	v_permlane32_swap_b32 v34, v194
	v_permlane32_swap_b32 v35, v195
	s_waitcnt lgkmcnt(2)
	v_mfma_f32_32x32x16_bf16 v[158:173], v[70:73], v[228:231], v[158:173]
	v_permlane32_swap_b32 v36, v196
	v_permlane32_swap_b32 v37, v197
	v_permlane32_swap_b32 v38, v198
	v_permlane32_swap_b32 v39, v199
	s_waitcnt lgkmcnt(1)
	v_mfma_f32_32x32x16_bf16 v[142:157], v[66:69], v[232:235], v[142:157]
	v_permlane32_swap_b32 v40, v200
	v_permlane32_swap_b32 v41, v201
	v_permlane32_swap_b32 v42, v202
	v_permlane32_swap_b32 v43, v203
	s_waitcnt lgkmcnt(0)
	v_mfma_f32_32x32x16_bf16 v[158:173], v[62:65], v[236:239], v[158:173]
	v_permlane32_swap_b32 v44, v204
	v_permlane32_swap_b32 v45, v205
	v_permlane32_swap_b32 v46, v206
	v_permlane32_swap_b32 v47, v207
	s_nop 1
	v_fma_f32 v0, -v131, v175, v0
	v_fma_f32 v32, v131, v174, v32
	v_fmac_f32_e32 v0, v252, v174
	v_fmac_f32_e32 v32, v252, v175
	v_cvt_pk_bf16_f32 v98, v0, v32
	ds_write_b32 v240, v98 offset:8192
	v_fma_f32 v1, -v131, v32, v1
	v_fma_f32 v33, v131, v0, v33
	v_fmac_f32_e32 v1, v252, v0
	v_fmac_f32_e32 v33, v252, v32
	v_cvt_pk_bf16_f32 v99, v1, v33
	ds_write_b32 v240, v99 offset:8464
	v_fma_f32 v2, -v131, v33, v2
	v_fma_f32 v34, v131, v1, v34
	v_fmac_f32_e32 v2, v252, v1
	v_fmac_f32_e32 v34, v252, v33
	v_cvt_pk_bf16_f32 v98, v2, v34
	ds_write_b32 v240, v98 offset:8736
	v_fma_f32 v3, -v131, v34, v3
	v_fma_f32 v35, v131, v2, v35
	v_fmac_f32_e32 v3, v252, v2
	v_fmac_f32_e32 v35, v252, v34
	v_cvt_pk_bf16_f32 v99, v3, v35
	ds_write_b32 v240, v99 offset:9008
	v_add_f32_e32 v242, v142, v158
	v_add_f32_e32 v243, v143, v159
	v_add_f32_e32 v60, v144, v160
	v_add_f32_e32 v61, v145, v161
	v_add_f32_e32 v116, v146, v162
	v_add_f32_e32 v117, v147, v163
	v_add_f32_e32 v100, v148, v164
	v_add_f32_e32 v128, v149, v165
	v_cvt_pk_bf16_f32 v242, v242, v243
	v_cvt_pk_bf16_f32 v243, v60, v61
	v_cvt_pk_bf16_f32 v60, v116, v117
	v_cvt_pk_bf16_f32 v61, v100, v128
	global_store_dwordx2 v[246:247], v[242:243], off
	global_store_dwordx2 v[246:247], v[60:61], off offset:16
	v_lshl_add_u64 v[246:247], v[246:247], 0, s[48:49]
	v_fma_f32 v16, -v131, v35, v16
	v_fma_f32 v192, v131, v3, v192
	v_fmac_f32_e32 v16, v252, v3
	v_fmac_f32_e32 v192, v252, v35
	v_cvt_pk_bf16_f32 v98, v16, v192
	ds_write_b32 v240, v98 offset:9280
	v_fma_f32 v17, -v131, v192, v17
	v_fma_f32 v193, v131, v16, v193
	v_fmac_f32_e32 v17, v252, v16
	v_fmac_f32_e32 v193, v252, v192
	v_cvt_pk_bf16_f32 v99, v17, v193
	ds_write_b32 v240, v99 offset:9552
	v_fma_f32 v18, -v131, v193, v18
	v_fma_f32 v194, v131, v17, v194
	v_fmac_f32_e32 v18, v252, v17
	v_fmac_f32_e32 v194, v252, v193
	v_cvt_pk_bf16_f32 v98, v18, v194
	ds_write_b32 v240, v98 offset:9824
	v_fma_f32 v19, -v131, v194, v19
	v_fma_f32 v195, v131, v18, v195
	v_fmac_f32_e32 v19, v252, v18
	v_fmac_f32_e32 v195, v252, v194
	v_cvt_pk_bf16_f32 v99, v19, v195
	ds_write_b32 v240, v99 offset:10096
	v_fma_f32 v4, -v131, v195, v4
	v_fma_f32 v36, v131, v19, v36
	v_fmac_f32_e32 v4, v252, v19
	v_fmac_f32_e32 v36, v252, v195
	v_cvt_pk_bf16_f32 v98, v4, v36
	ds_write_b32 v240, v98 offset:10368
	v_fma_f32 v5, -v131, v36, v5
	v_fma_f32 v37, v131, v4, v37
	v_fmac_f32_e32 v5, v252, v4
	v_fmac_f32_e32 v37, v252, v36
	v_cvt_pk_bf16_f32 v99, v5, v37
	ds_write_b32 v240, v99 offset:10640
	v_fma_f32 v6, -v131, v37, v6
	v_fma_f32 v38, v131, v5, v38
	v_fmac_f32_e32 v6, v252, v5
	v_fmac_f32_e32 v38, v252, v37
	v_cvt_pk_bf16_f32 v98, v6, v38
	ds_write_b32 v240, v98 offset:10912
	v_fma_f32 v7, -v131, v38, v7
	v_fma_f32 v39, v131, v6, v39
	v_fmac_f32_e32 v7, v252, v6
	v_fmac_f32_e32 v39, v252, v38
	v_cvt_pk_bf16_f32 v99, v7, v39
	ds_write_b32 v240, v99 offset:11184
	v_fma_f32 v20, -v131, v39, v20
	v_fma_f32 v196, v131, v7, v196
	v_fmac_f32_e32 v20, v252, v7
	v_fmac_f32_e32 v196, v252, v39
	v_cvt_pk_bf16_f32 v98, v20, v196
	ds_write_b32 v240, v98 offset:11456
	v_fma_f32 v21, -v131, v196, v21
	v_fma_f32 v197, v131, v20, v197
	v_fmac_f32_e32 v21, v252, v20
	v_fmac_f32_e32 v197, v252, v196
	v_cvt_pk_bf16_f32 v99, v21, v197
	ds_write_b32 v240, v99 offset:11728
	v_fma_f32 v22, -v131, v197, v22
	v_fma_f32 v198, v131, v21, v198
	v_fmac_f32_e32 v22, v252, v21
	v_fmac_f32_e32 v198, v252, v197
	v_cvt_pk_bf16_f32 v98, v22, v198
	ds_write_b32 v240, v98 offset:12000
	v_fma_f32 v23, -v131, v198, v23
	v_fma_f32 v199, v131, v22, v199
	v_fmac_f32_e32 v23, v252, v22
	v_fmac_f32_e32 v199, v252, v198
	v_cvt_pk_bf16_f32 v99, v23, v199
	ds_write_b32 v240, v99 offset:12272
	v_fma_f32 v8, -v131, v199, v8
	v_fma_f32 v40, v131, v23, v40
	v_fmac_f32_e32 v8, v252, v23
	v_fmac_f32_e32 v40, v252, v199
	v_cvt_pk_bf16_f32 v98, v8, v40
	ds_write_b32 v240, v98 offset:12544
	v_fma_f32 v9, -v131, v40, v9
	v_fma_f32 v41, v131, v8, v41
	v_fmac_f32_e32 v9, v252, v8
	v_fmac_f32_e32 v41, v252, v40
	v_cvt_pk_bf16_f32 v99, v9, v41
	ds_write_b32 v240, v99 offset:12816
	v_fma_f32 v10, -v131, v41, v10
	v_fma_f32 v42, v131, v9, v42
	v_fmac_f32_e32 v10, v252, v9
	v_fmac_f32_e32 v42, v252, v41
	v_cvt_pk_bf16_f32 v98, v10, v42
	ds_write_b32 v240, v98 offset:13088
	v_fma_f32 v11, -v131, v42, v11
	v_fma_f32 v43, v131, v10, v43
	v_fmac_f32_e32 v11, v252, v10
	v_fmac_f32_e32 v43, v252, v42
	v_cvt_pk_bf16_f32 v99, v11, v43
	ds_write_b32 v240, v99 offset:13360
	v_fma_f32 v24, -v131, v43, v24
	v_fma_f32 v200, v131, v11, v200
	v_fmac_f32_e32 v24, v252, v11
	v_fmac_f32_e32 v200, v252, v43
	v_cvt_pk_bf16_f32 v98, v24, v200
	ds_write_b32 v240, v98 offset:13632
	v_fma_f32 v25, -v131, v200, v25
	v_fma_f32 v201, v131, v24, v201
	v_fmac_f32_e32 v25, v252, v24
	v_fmac_f32_e32 v201, v252, v200
	v_cvt_pk_bf16_f32 v99, v25, v201
	ds_write_b32 v240, v99 offset:13904
	v_fma_f32 v26, -v131, v201, v26
	v_fma_f32 v202, v131, v25, v202
	v_fmac_f32_e32 v26, v252, v25
	v_fmac_f32_e32 v202, v252, v201
	v_cvt_pk_bf16_f32 v98, v26, v202
	ds_write_b32 v240, v98 offset:14176
	v_fma_f32 v27, -v131, v202, v27
	v_fma_f32 v203, v131, v26, v203
	v_fmac_f32_e32 v27, v252, v26
	v_fmac_f32_e32 v203, v252, v202
	v_cvt_pk_bf16_f32 v99, v27, v203
	ds_write_b32 v240, v99 offset:14448
	v_fma_f32 v12, -v131, v203, v12
	v_fma_f32 v44, v131, v27, v44
	v_fmac_f32_e32 v12, v252, v27
	v_fmac_f32_e32 v44, v252, v203
	v_cvt_pk_bf16_f32 v98, v12, v44
	ds_write_b32 v240, v98 offset:14720
	v_fma_f32 v13, -v131, v44, v13
	v_fma_f32 v45, v131, v12, v45
	v_fmac_f32_e32 v13, v252, v12
	v_fmac_f32_e32 v45, v252, v44
	v_cvt_pk_bf16_f32 v99, v13, v45
	ds_write_b32 v240, v99 offset:14992
	v_fma_f32 v14, -v131, v45, v14
	v_fma_f32 v46, v131, v13, v46
	v_fmac_f32_e32 v14, v252, v13
	v_fmac_f32_e32 v46, v252, v45
	v_cvt_pk_bf16_f32 v98, v14, v46
	ds_write_b32 v240, v98 offset:15264
	v_fma_f32 v15, -v131, v46, v15
	v_fma_f32 v47, v131, v14, v47
	v_fmac_f32_e32 v15, v252, v14
	v_fmac_f32_e32 v47, v252, v46
	v_cvt_pk_bf16_f32 v99, v15, v47
	ds_write_b32 v240, v99 offset:15536
	v_fma_f32 v28, -v131, v47, v28
	v_fma_f32 v204, v131, v15, v204
	v_fmac_f32_e32 v28, v252, v15
	v_fmac_f32_e32 v204, v252, v47
	v_cvt_pk_bf16_f32 v98, v28, v204
	ds_write_b32 v240, v98 offset:15808
	v_fma_f32 v29, -v131, v204, v29
	v_fma_f32 v205, v131, v28, v205
	v_fmac_f32_e32 v29, v252, v28
	v_fmac_f32_e32 v205, v252, v204
	v_cvt_pk_bf16_f32 v99, v29, v205
	ds_write_b32 v240, v99 offset:16080
	v_fma_f32 v30, -v131, v205, v30
	v_fma_f32 v206, v131, v29, v206
	v_fmac_f32_e32 v30, v252, v29
	v_fmac_f32_e32 v206, v252, v205
	v_cvt_pk_bf16_f32 v98, v30, v206
	ds_write_b32 v240, v98 offset:16352
	v_fma_f32 v174, -v131, v206, v31
	v_fma_f32 v175, v131, v30, v207
	v_fmac_f32_e32 v174, v252, v30
	v_fmac_f32_e32 v175, v252, v206
	v_cvt_pk_bf16_f32 v99, v174, v175
	ds_write_b32 v240, v99 offset:16624
	s_waitcnt vmcnt(8)
	s_cmp_lt_u32 s77, s39
	s_cselect_b32 s46, s48, 0
	s_cselect_b32 s47, s49, 0
	s_add_i32 s77, s77, 1
	v_lshl_add_u64 v[244:245], v[244:245], 0, s[46:47]
	global_load_dwordx4 v[248:251], v[244:245], off
	v_mfma_f32_32x32x16_bf16 v[0:15], v[48:51], v[110:113], 0
	v_mfma_f32_32x32x16_bf16 v[16:31], v[48:51], v[102:105], 0
	v_mfma_f32_32x32x16_bf16 v[32:47], v[48:51], v[106:109], 0
	v_mfma_f32_32x32x16_bf16 v[192:207], v[48:51], v[94:97], 0
	ds_read_b128 v[208:211], v241 offset:8192
	ds_read_b128 v[212:215], v241 offset:8224
	ds_read_b128 v[216:219], v241 offset:8256
	ds_read_b128 v[220:223], v241 offset:8288
	ds_read_b128 v[224:227], v241 offset:8320
	ds_read_b128 v[228:231], v241 offset:8352
	ds_read_b128 v[232:235], v241 offset:8384
	ds_read_b128 v[236:239], v241 offset:8416
	s_waitcnt lgkmcnt(7)
	v_mfma_f32_32x32x16_bf16 v[142:157], v[90:93], v[208:211], 0
	v_permlane32_swap_b32 v0, v16
	v_permlane32_swap_b32 v1, v17
	v_permlane32_swap_b32 v2, v18
	v_permlane32_swap_b32 v3, v19
	s_waitcnt lgkmcnt(6)
	v_mfma_f32_32x32x16_bf16 v[158:173], v[86:89], v[212:215], 0
	v_permlane32_swap_b32 v4, v20
	v_permlane32_swap_b32 v5, v21
	v_permlane32_swap_b32 v6, v22
	v_permlane32_swap_b32 v7, v23
	s_waitcnt lgkmcnt(5)
	v_mfma_f32_32x32x16_bf16 v[142:157], v[82:85], v[216:219], v[142:157]
	v_permlane32_swap_b32 v8, v24
	v_permlane32_swap_b32 v9, v25
	v_permlane32_swap_b32 v10, v26
	v_permlane32_swap_b32 v11, v27
	s_waitcnt lgkmcnt(4)
	v_mfma_f32_32x32x16_bf16 v[158:173], v[78:81], v[220:223], v[158:173]
	v_permlane32_swap_b32 v12, v28
	v_permlane32_swap_b32 v13, v29
	v_permlane32_swap_b32 v14, v30
	v_permlane32_swap_b32 v15, v31
	s_waitcnt lgkmcnt(3)
	v_mfma_f32_32x32x16_bf16 v[142:157], v[74:77], v[224:227], v[142:157]
	v_permlane32_swap_b32 v32, v192
	v_permlane32_swap_b32 v33, v193
	v_permlane32_swap_b32 v34, v194
	v_permlane32_swap_b32 v35, v195
	s_waitcnt lgkmcnt(2)
	v_mfma_f32_32x32x16_bf16 v[158:173], v[70:73], v[228:231], v[158:173]
	v_permlane32_swap_b32 v36, v196
	v_permlane32_swap_b32 v37, v197
	v_permlane32_swap_b32 v38, v198
	v_permlane32_swap_b32 v39, v199
	s_waitcnt lgkmcnt(1)
	v_mfma_f32_32x32x16_bf16 v[142:157], v[66:69], v[232:235], v[142:157]
	v_permlane32_swap_b32 v40, v200
	v_permlane32_swap_b32 v41, v201
	v_permlane32_swap_b32 v42, v202
	v_permlane32_swap_b32 v43, v203
	s_waitcnt lgkmcnt(0)
	v_mfma_f32_32x32x16_bf16 v[158:173], v[62:65], v[236:239], v[158:173]
	v_permlane32_swap_b32 v44, v204
	v_permlane32_swap_b32 v45, v205
	v_permlane32_swap_b32 v46, v206
	v_permlane32_swap_b32 v47, v207
	s_add_i32 s76, s76, 4
	s_cmp_lt_u32 s76, s39
	s_cbranch_scc1 .Lscf_loop
	s_nop 15
	v_add_f32_e32 v242, v142, v158
	v_add_f32_e32 v243, v143, v159
	v_add_f32_e32 v60, v144, v160
	v_add_f32_e32 v61, v145, v161
	v_add_f32_e32 v116, v146, v162
	v_add_f32_e32 v117, v147, v163
	v_add_f32_e32 v100, v148, v164
	v_add_f32_e32 v128, v149, v165
	v_cvt_pk_bf16_f32 v242, v242, v243
	v_cvt_pk_bf16_f32 v243, v60, v61
	v_cvt_pk_bf16_f32 v60, v116, v117
	v_cvt_pk_bf16_f32 v61, v100, v128
	global_store_dwordx2 v[246:247], v[242:243], off
	global_store_dwordx2 v[246:247], v[60:61], off offset:16
	v_lshl_add_u64 v[246:247], v[246:247], 0, s[48:49]
	v_mov_b32_e32 v135, v174
	v_mov_b32_e32 v101, v175
	s_branch .LBB0_631
